# EpiResid epilogues (FFN down, out-proj): the 64 xor-16/xor-32 row-sum ds_bpermute round trips replaced by v_permlane16/32_swap of (copy, value) (bit-identical); on top of v056
# baseline (speedup 1.0000x reference)
.LBB0_409:
	s_ashr_i32 s51, s50, 31
	s_lshl_b64 s[28:29], s[50:51], 19
	s_add_u32 s60, s0, s28
	s_addc_u32 s61, s1, s29
	v_lshl_add_u32 v144, s2, 8, v161
	v_lshl_add_u64 v[156:157], v[144:145], 1, s[60:61]
	global_load_dwordx2 v[174:175], v[156:157], off
	global_load_dwordx2 v[176:177], v[156:157], off offset:32
	global_load_dwordx2 v[178:179], v[156:157], off offset:256
	global_load_dwordx2 v[158:159], v[156:157], off offset:288
	v_and_b32_e32 v139, 64, v183
	v_xor_b32_e32 v138, 16, v183
	v_add_u32_e32 v139, 64, v139
	v_cmp_lt_i32_e32 vcc, v138, v139
	v_add_u32_e32 v144, 0x4000, v144
	s_waitcnt vmcnt(0)
	v_lshlrev_b32_e32 v180, 16, v174
	v_cndmask_b32_e32 v138, v183, v138, vcc
	v_lshlrev_b32_e32 v173, 2, v138
	v_xor_b32_e32 v138, 32, v183
	v_cmp_lt_i32_e32 vcc, v138, v139
	v_and_b32_e32 v181, 0xffff0000, v174
	v_lshlrev_b32_e32 v174, 16, v175
	v_cndmask_b32_e32 v138, v183, v138, vcc
	v_lshlrev_b32_e32 v172, 2, v138
	v_lshl_add_u64 v[138:139], v[144:145], 1, s[60:61]
	global_load_dwordx2 v[154:155], v[138:139], off
	global_load_dwordx2 v[142:143], v[138:139], off offset:32
	global_load_dwordx2 v[140:141], v[138:139], off offset:256
	s_nop 0
	global_load_dwordx2 v[138:139], v[138:139], off offset:288
	v_and_b32_e32 v175, 0xffff0000, v175
	v_pk_fma_f32 v[124:125], v[124:125], 0.5, v[180:181] op_sel_hi:[1,0,1]
	v_pk_fma_f32 v[126:127], v[126:127], 0.5, v[174:175] op_sel_hi:[1,0,1]
	v_mul_f32_e32 v174, v125, v125
	v_fmac_f32_e32 v174, v124, v124
	v_cvt_pk_bf16_f32 v124, v124, v125
	v_cvt_pk_bf16_f32 v125, v126, v127
	v_mul_f32_e32 v175, v127, v127
	global_store_dwordx2 v[156:157], v[124:125], off
	v_lshlrev_b32_e32 v124, 16, v176
	v_and_b32_e32 v125, 0xffff0000, v176
	v_fmac_f32_e32 v175, v126, v126
	v_lshlrev_b32_e32 v126, 16, v177
	v_and_b32_e32 v127, 0xffff0000, v177
	v_pk_fma_f32 v[120:121], v[120:121], 0.5, v[124:125] op_sel_hi:[1,0,1]
	v_pk_fma_f32 v[122:123], v[122:123], 0.5, v[126:127] op_sel_hi:[1,0,1]
	v_mul_f32_e32 v124, v121, v121
	v_fmac_f32_e32 v124, v120, v120
	v_cvt_pk_bf16_f32 v120, v120, v121
	v_cvt_pk_bf16_f32 v121, v122, v123
	v_mul_f32_e32 v125, v123, v123
	global_store_dwordx2 v[156:157], v[120:121], off offset:32
	v_lshlrev_b32_e32 v120, 16, v178
	v_and_b32_e32 v121, 0xffff0000, v178
	v_fmac_f32_e32 v125, v122, v122
	v_lshlrev_b32_e32 v122, 16, v179
	v_and_b32_e32 v123, 0xffff0000, v179
	v_pk_fma_f32 v[116:117], v[116:117], 0.5, v[120:121] op_sel_hi:[1,0,1]
	v_pk_fma_f32 v[118:119], v[118:119], 0.5, v[122:123] op_sel_hi:[1,0,1]
	v_mul_f32_e32 v120, v117, v117
	v_fmac_f32_e32 v120, v116, v116
	v_mul_f32_e32 v121, v119, v119
	v_cvt_pk_bf16_f32 v116, v116, v117
	v_cvt_pk_bf16_f32 v117, v118, v119
	v_fmac_f32_e32 v121, v118, v118
	global_store_dwordx2 v[156:157], v[116:117], off offset:256
	v_lshlrev_b32_e32 v116, 16, v158
	v_and_b32_e32 v117, 0xffff0000, v158
	v_lshlrev_b32_e32 v118, 16, v159
	v_and_b32_e32 v119, 0xffff0000, v159
	v_pk_fma_f32 v[114:115], v[114:115], 0.5, v[118:119] op_sel_hi:[1,0,1]
	v_pk_fma_f32 v[112:113], v[112:113], 0.5, v[116:117] op_sel_hi:[1,0,1]
	v_add_f32_e32 v174, v174, v175
	v_add_f32_e32 v124, v124, v125
	v_mul_f32_e32 v116, v113, v113
	v_mul_f32_e32 v117, v115, v115
	v_add_f32_e32 v124, v174, v124
	v_add_f32_e32 v120, v120, v121
	v_fmac_f32_e32 v116, v112, v112
	v_fmac_f32_e32 v117, v114, v114
	v_add_f32_e32 v120, v124, v120
	v_add_f32_e32 v116, v116, v117
	v_add_f32_e32 v116, v120, v116
	v_cvt_pk_bf16_f32 v112, v112, v113
	v_cvt_pk_bf16_f32 v113, v114, v115
	global_store_dwordx2 v[156:157], v[112:113], off offset:288
	v_mov_b32_e32 v112, v116
	s_nop 1
	v_permlane16_swap_b32_e32 v112, v116
	s_waitcnt lgkmcnt(0)
	v_add_f32_e32 v112, v116, v112
	v_mov_b32_e32 v113, v112
	s_nop 1
	v_permlane32_swap_b32_e32 v113, v112
	s_and_saveexec_b64 s[28:29], s[38:39]
	s_cbranch_execz .LBB0_411
	s_waitcnt lgkmcnt(0)
	v_add_f32_e32 v112, v112, v113
	ds_write_b32 v162, v112
.LBB0_411:
	s_or_b64 exec, exec, s[28:29]
	v_mov_b32_e32 v121, v145
	v_add_u32_e32 v120, 0x4000, v144
	s_waitcnt lgkmcnt(0)
	v_lshl_add_u64 v[112:113], v[120:121], 1, s[60:61]
	global_load_dwordx2 v[118:119], v[112:113], off
	global_load_dwordx2 v[116:117], v[112:113], off offset:32
	global_load_dwordx2 v[114:115], v[112:113], off offset:256
	s_nop 0
	global_load_dwordx2 v[112:113], v[112:113], off offset:288
	s_waitcnt vmcnt(11)
	v_lshlrev_b32_e32 v124, 16, v154
	v_and_b32_e32 v125, 0xffff0000, v154
	v_lshlrev_b32_e32 v126, 16, v155
	v_and_b32_e32 v127, 0xffff0000, v155
	v_pk_fma_f32 v[108:109], v[108:109], 0.5, v[124:125] op_sel_hi:[1,0,1]
	v_pk_fma_f32 v[110:111], v[110:111], 0.5, v[126:127] op_sel_hi:[1,0,1]
	v_mul_f32_e32 v121, v109, v109
	v_lshl_add_u64 v[122:123], v[144:145], 1, s[60:61]
	v_fmac_f32_e32 v121, v108, v108
	v_mul_f32_e32 v124, v111, v111
	v_cvt_pk_bf16_f32 v108, v108, v109
	v_cvt_pk_bf16_f32 v109, v110, v111
	v_fmac_f32_e32 v124, v110, v110
	global_store_dwordx2 v[122:123], v[108:109], off
	s_waitcnt vmcnt(11)
	v_lshlrev_b32_e32 v108, 16, v142
	v_and_b32_e32 v109, 0xffff0000, v142
	v_lshlrev_b32_e32 v110, 16, v143
	v_and_b32_e32 v111, 0xffff0000, v143
	v_pk_fma_f32 v[106:107], v[106:107], 0.5, v[110:111] op_sel_hi:[1,0,1]
	v_pk_fma_f32 v[104:105], v[104:105], 0.5, v[108:109] op_sel_hi:[1,0,1]
	v_mul_f32_e32 v109, v107, v107
	v_mul_f32_e32 v108, v105, v105
	v_fmac_f32_e32 v108, v104, v104
	v_fmac_f32_e32 v109, v106, v106
	v_add_f32_e32 v121, v121, v124
	v_add_f32_e32 v108, v108, v109
	v_add_f32_e32 v121, v121, v108
	s_waitcnt vmcnt(10)
	v_lshlrev_b32_e32 v108, 16, v140
	v_and_b32_e32 v109, 0xffff0000, v140
	v_lshlrev_b32_e32 v110, 16, v141
	v_and_b32_e32 v111, 0xffff0000, v141
	v_pk_fma_f32 v[102:103], v[102:103], 0.5, v[110:111] op_sel_hi:[1,0,1]
	v_pk_fma_f32 v[100:101], v[100:101], 0.5, v[108:109] op_sel_hi:[1,0,1]
	v_cvt_pk_bf16_f32 v104, v104, v105
	v_mul_f32_e32 v105, v101, v101
	v_mul_f32_e32 v108, v103, v103
	v_fmac_f32_e32 v105, v100, v100
	v_fmac_f32_e32 v108, v102, v102
	v_add_f32_e32 v105, v105, v108
	s_waitcnt vmcnt(9)
	v_lshlrev_b32_e32 v108, 16, v138
	v_and_b32_e32 v109, 0xffff0000, v138
	v_lshlrev_b32_e32 v110, 16, v139
	v_and_b32_e32 v111, 0xffff0000, v139
	v_pk_fma_f32 v[98:99], v[98:99], 0.5, v[110:111] op_sel_hi:[1,0,1]
	v_pk_fma_f32 v[108:109], v[96:97], 0.5, v[108:109] op_sel_hi:[1,0,1]
	v_mul_f32_e32 v97, v99, v99
	v_mul_f32_e32 v96, v109, v109
	v_fmac_f32_e32 v96, v108, v108
	v_fmac_f32_e32 v97, v98, v98
	v_add_f32_e32 v105, v121, v105
	v_add_f32_e32 v96, v96, v97
	v_add_f32_e32 v96, v105, v96
	v_mov_b32_e32 v97, v96
	s_nop 1
	v_permlane16_swap_b32_e32 v97, v96
	v_cvt_pk_bf16_f32 v100, v100, v101
	v_cvt_pk_bf16_f32 v101, v102, v103
	v_cvt_pk_bf16_f32 v105, v106, v107
	global_store_dwordx2 v[122:123], v[100:101], off offset:256
	s_waitcnt lgkmcnt(0)
	v_add_f32_e32 v96, v96, v97
	v_mov_b32_e32 v97, v96
	s_nop 1
	v_permlane32_swap_b32_e32 v97, v96
	v_cvt_pk_bf16_f32 v100, v108, v109
	v_cvt_pk_bf16_f32 v101, v98, v99
	global_store_dwordx2 v[122:123], v[104:105], off offset:32
	global_store_dwordx2 v[122:123], v[100:101], off offset:288
	s_and_saveexec_b64 s[28:29], s[38:39]
	s_cbranch_execz .LBB0_413
	s_waitcnt lgkmcnt(0)
	v_add_f32_e32 v96, v96, v97
	ds_write_b32 v163, v96
.LBB0_413:
	s_or_b64 exec, exec, s[28:29]
	s_waitcnt vmcnt(7)
	v_lshlrev_b32_e32 v106, 16, v118
	v_add_u32_e32 v144, 0x4000, v120
	s_waitcnt lgkmcnt(0)
	v_lshl_add_u64 v[96:97], v[144:145], 1, s[60:61]
	global_load_dwordx2 v[102:103], v[96:97], off
	global_load_dwordx2 v[100:101], v[96:97], off offset:32
	global_load_dwordx2 v[98:99], v[96:97], off offset:256
	s_nop 0
	global_load_dwordx2 v[96:97], v[96:97], off offset:288
	v_and_b32_e32 v107, 0xffff0000, v118
	v_lshlrev_b32_e32 v108, 16, v119
	v_and_b32_e32 v109, 0xffff0000, v119
	v_pk_fma_f32 v[92:93], v[92:93], 0.5, v[106:107] op_sel_hi:[1,0,1]
	v_mov_b32_e32 v121, v145
	v_pk_fma_f32 v[94:95], v[94:95], 0.5, v[108:109] op_sel_hi:[1,0,1]
	v_mul_f32_e32 v106, v93, v93
	v_lshl_add_u64 v[104:105], v[120:121], 1, s[60:61]
	v_fmac_f32_e32 v106, v92, v92
	v_mul_f32_e32 v107, v95, v95
	v_cvt_pk_bf16_f32 v92, v92, v93
	v_cvt_pk_bf16_f32 v93, v94, v95
	v_fmac_f32_e32 v107, v94, v94
	global_store_dwordx2 v[104:105], v[92:93], off
	s_waitcnt vmcnt(11)
	v_lshlrev_b32_e32 v92, 16, v116
	v_and_b32_e32 v93, 0xffff0000, v116
	v_lshlrev_b32_e32 v94, 16, v117
	v_and_b32_e32 v95, 0xffff0000, v117
	v_pk_fma_f32 v[90:91], v[90:91], 0.5, v[94:95] op_sel_hi:[1,0,1]
	v_pk_fma_f32 v[88:89], v[88:89], 0.5, v[92:93] op_sel_hi:[1,0,1]
	v_mul_f32_e32 v93, v91, v91
	v_mul_f32_e32 v92, v89, v89
	v_fmac_f32_e32 v92, v88, v88
	v_fmac_f32_e32 v93, v90, v90
	v_add_f32_e32 v106, v106, v107
	v_add_f32_e32 v92, v92, v93
	v_add_f32_e32 v106, v106, v92
	s_waitcnt vmcnt(10)
	v_lshlrev_b32_e32 v92, 16, v114
	v_and_b32_e32 v93, 0xffff0000, v114
	v_lshlrev_b32_e32 v94, 16, v115
	v_and_b32_e32 v95, 0xffff0000, v115
	v_pk_fma_f32 v[86:87], v[86:87], 0.5, v[94:95] op_sel_hi:[1,0,1]
	v_pk_fma_f32 v[84:85], v[84:85], 0.5, v[92:93] op_sel_hi:[1,0,1]
	v_cvt_pk_bf16_f32 v88, v88, v89
	v_mul_f32_e32 v89, v85, v85
	v_mul_f32_e32 v92, v87, v87
	v_fmac_f32_e32 v89, v84, v84
	v_fmac_f32_e32 v92, v86, v86
	v_add_f32_e32 v89, v89, v92
	s_waitcnt vmcnt(9)
	v_lshlrev_b32_e32 v92, 16, v112
	v_and_b32_e32 v93, 0xffff0000, v112
	v_lshlrev_b32_e32 v94, 16, v113
	v_and_b32_e32 v95, 0xffff0000, v113
	v_pk_fma_f32 v[82:83], v[82:83], 0.5, v[94:95] op_sel_hi:[1,0,1]
	v_pk_fma_f32 v[92:93], v[80:81], 0.5, v[92:93] op_sel_hi:[1,0,1]
	v_mul_f32_e32 v81, v83, v83
	v_mul_f32_e32 v80, v93, v93
	v_fmac_f32_e32 v80, v92, v92
	v_fmac_f32_e32 v81, v82, v82
	v_add_f32_e32 v89, v106, v89
	v_add_f32_e32 v80, v80, v81
	v_add_f32_e32 v80, v89, v80
	v_mov_b32_e32 v81, v80
	s_nop 1
	v_permlane16_swap_b32_e32 v81, v80
	v_cvt_pk_bf16_f32 v84, v84, v85
	v_cvt_pk_bf16_f32 v85, v86, v87
	v_cvt_pk_bf16_f32 v89, v90, v91
	global_store_dwordx2 v[104:105], v[84:85], off offset:256
	s_waitcnt lgkmcnt(0)
	v_add_f32_e32 v80, v80, v81
	v_mov_b32_e32 v81, v80
	s_nop 1
	v_permlane32_swap_b32_e32 v81, v80
	v_cvt_pk_bf16_f32 v84, v92, v93
	v_cvt_pk_bf16_f32 v85, v82, v83
	global_store_dwordx2 v[104:105], v[88:89], off offset:32
	global_store_dwordx2 v[104:105], v[84:85], off offset:288
	s_and_saveexec_b64 s[28:29], s[38:39]
	s_cbranch_execz .LBB0_415
	s_waitcnt lgkmcnt(0)
	v_add_f32_e32 v80, v80, v81
	ds_write_b32 v164, v80
.LBB0_415:
	s_or_b64 exec, exec, s[28:29]
	v_mov_b32_e32 v89, v145
	v_add_u32_e32 v88, 0x14000, v144
	s_waitcnt lgkmcnt(0)
	v_lshl_add_u64 v[80:81], v[88:89], 1, s[60:61]
	global_load_dwordx2 v[86:87], v[80:81], off
	global_load_dwordx2 v[84:85], v[80:81], off offset:32
	global_load_dwordx2 v[82:83], v[80:81], off offset:256
	s_nop 0
	global_load_dwordx2 v[80:81], v[80:81], off offset:288
	s_waitcnt vmcnt(11)
	v_lshlrev_b32_e32 v92, 16, v102
	v_and_b32_e32 v93, 0xffff0000, v102
	v_lshlrev_b32_e32 v94, 16, v103
	v_and_b32_e32 v95, 0xffff0000, v103
	v_pk_fma_f32 v[76:77], v[76:77], 0.5, v[92:93] op_sel_hi:[1,0,1]
	v_pk_fma_f32 v[78:79], v[78:79], 0.5, v[94:95] op_sel_hi:[1,0,1]
	v_mul_f32_e32 v89, v77, v77
	v_lshl_add_u64 v[90:91], v[144:145], 1, s[60:61]
	v_fmac_f32_e32 v89, v76, v76
	v_mul_f32_e32 v92, v79, v79
	v_cvt_pk_bf16_f32 v76, v76, v77
	v_cvt_pk_bf16_f32 v77, v78, v79
	v_fmac_f32_e32 v92, v78, v78
	global_store_dwordx2 v[90:91], v[76:77], off
	s_waitcnt vmcnt(11)
	v_lshlrev_b32_e32 v76, 16, v100
	v_and_b32_e32 v77, 0xffff0000, v100
	v_lshlrev_b32_e32 v78, 16, v101
	v_and_b32_e32 v79, 0xffff0000, v101
	v_pk_fma_f32 v[74:75], v[74:75], 0.5, v[78:79] op_sel_hi:[1,0,1]
	v_pk_fma_f32 v[72:73], v[72:73], 0.5, v[76:77] op_sel_hi:[1,0,1]
	v_mul_f32_e32 v77, v75, v75
	v_mul_f32_e32 v76, v73, v73
	v_fmac_f32_e32 v76, v72, v72
	v_fmac_f32_e32 v77, v74, v74
	v_add_f32_e32 v89, v89, v92
	v_add_f32_e32 v76, v76, v77
	v_add_f32_e32 v89, v89, v76
	s_waitcnt vmcnt(10)
	v_lshlrev_b32_e32 v76, 16, v98
	v_and_b32_e32 v77, 0xffff0000, v98
	v_lshlrev_b32_e32 v78, 16, v99
	v_and_b32_e32 v79, 0xffff0000, v99
	v_pk_fma_f32 v[70:71], v[70:71], 0.5, v[78:79] op_sel_hi:[1,0,1]
	v_pk_fma_f32 v[68:69], v[68:69], 0.5, v[76:77] op_sel_hi:[1,0,1]
	v_cvt_pk_bf16_f32 v72, v72, v73
	v_mul_f32_e32 v73, v69, v69
	v_mul_f32_e32 v76, v71, v71
	v_fmac_f32_e32 v73, v68, v68
	v_fmac_f32_e32 v76, v70, v70
	v_add_f32_e32 v73, v73, v76
	s_waitcnt vmcnt(9)
	v_lshlrev_b32_e32 v76, 16, v96
	v_and_b32_e32 v77, 0xffff0000, v96
	v_lshlrev_b32_e32 v78, 16, v97
	v_and_b32_e32 v79, 0xffff0000, v97
	v_pk_fma_f32 v[66:67], v[66:67], 0.5, v[78:79] op_sel_hi:[1,0,1]
	v_pk_fma_f32 v[76:77], v[64:65], 0.5, v[76:77] op_sel_hi:[1,0,1]
	v_mul_f32_e32 v65, v67, v67
	v_mul_f32_e32 v64, v77, v77
	v_fmac_f32_e32 v64, v76, v76
	v_fmac_f32_e32 v65, v66, v66
	v_add_f32_e32 v73, v89, v73
	v_add_f32_e32 v64, v64, v65
	v_add_f32_e32 v64, v73, v64
	v_mov_b32_e32 v65, v64
	s_nop 1
	v_permlane16_swap_b32_e32 v65, v64
	v_cvt_pk_bf16_f32 v68, v68, v69
	v_cvt_pk_bf16_f32 v69, v70, v71
	v_cvt_pk_bf16_f32 v73, v74, v75
	global_store_dwordx2 v[90:91], v[68:69], off offset:256
	s_waitcnt lgkmcnt(0)
	v_add_f32_e32 v64, v64, v65
	v_mov_b32_e32 v65, v64
	s_nop 1
	v_permlane32_swap_b32_e32 v65, v64
	v_cvt_pk_bf16_f32 v68, v76, v77
	v_cvt_pk_bf16_f32 v69, v66, v67
	global_store_dwordx2 v[90:91], v[72:73], off offset:32
	global_store_dwordx2 v[90:91], v[68:69], off offset:288
	s_and_saveexec_b64 s[28:29], s[38:39]
	s_cbranch_execz .LBB0_417
	s_waitcnt lgkmcnt(0)
	v_add_f32_e32 v64, v64, v65
	ds_write_b32 v165, v64
.LBB0_417:
	s_or_b64 exec, exec, s[28:29]
	s_waitcnt vmcnt(7)
	v_lshlrev_b32_e32 v74, 16, v86
	v_add_u32_e32 v144, 0x4000, v88
	s_waitcnt lgkmcnt(0)
	v_lshl_add_u64 v[64:65], v[144:145], 1, s[60:61]
	global_load_dwordx2 v[70:71], v[64:65], off
	global_load_dwordx2 v[68:69], v[64:65], off offset:32
	global_load_dwordx2 v[66:67], v[64:65], off offset:256
	s_nop 0
	global_load_dwordx2 v[64:65], v[64:65], off offset:288
	v_and_b32_e32 v75, 0xffff0000, v86
	v_lshlrev_b32_e32 v76, 16, v87
	v_and_b32_e32 v77, 0xffff0000, v87
	v_pk_fma_f32 v[60:61], v[60:61], 0.5, v[74:75] op_sel_hi:[1,0,1]
	v_mov_b32_e32 v89, v145
	v_pk_fma_f32 v[62:63], v[62:63], 0.5, v[76:77] op_sel_hi:[1,0,1]
	v_mul_f32_e32 v74, v61, v61
	v_lshl_add_u64 v[72:73], v[88:89], 1, s[60:61]
	v_fmac_f32_e32 v74, v60, v60
	v_mul_f32_e32 v75, v63, v63
	v_cvt_pk_bf16_f32 v60, v60, v61
	v_cvt_pk_bf16_f32 v61, v62, v63
	v_fmac_f32_e32 v75, v62, v62
	global_store_dwordx2 v[72:73], v[60:61], off
	s_waitcnt vmcnt(11)
	v_lshlrev_b32_e32 v60, 16, v84
	v_and_b32_e32 v61, 0xffff0000, v84
	v_lshlrev_b32_e32 v62, 16, v85
	v_and_b32_e32 v63, 0xffff0000, v85
	v_pk_fma_f32 v[58:59], v[58:59], 0.5, v[62:63] op_sel_hi:[1,0,1]
	v_pk_fma_f32 v[56:57], v[56:57], 0.5, v[60:61] op_sel_hi:[1,0,1]
	v_mul_f32_e32 v61, v59, v59
	v_mul_f32_e32 v60, v57, v57
	v_fmac_f32_e32 v60, v56, v56
	v_fmac_f32_e32 v61, v58, v58
	v_add_f32_e32 v74, v74, v75
	v_add_f32_e32 v60, v60, v61
	v_add_f32_e32 v74, v74, v60
	s_waitcnt vmcnt(10)
	v_lshlrev_b32_e32 v60, 16, v82
	v_and_b32_e32 v61, 0xffff0000, v82
	v_lshlrev_b32_e32 v62, 16, v83
	v_and_b32_e32 v63, 0xffff0000, v83
	v_pk_fma_f32 v[54:55], v[54:55], 0.5, v[62:63] op_sel_hi:[1,0,1]
	v_pk_fma_f32 v[52:53], v[52:53], 0.5, v[60:61] op_sel_hi:[1,0,1]
	v_cvt_pk_bf16_f32 v56, v56, v57
	v_mul_f32_e32 v57, v53, v53
	v_mul_f32_e32 v60, v55, v55
	v_fmac_f32_e32 v57, v52, v52
	v_fmac_f32_e32 v60, v54, v54
	v_add_f32_e32 v57, v57, v60
	s_waitcnt vmcnt(9)
	v_lshlrev_b32_e32 v60, 16, v80
	v_and_b32_e32 v61, 0xffff0000, v80
	v_lshlrev_b32_e32 v62, 16, v81
	v_and_b32_e32 v63, 0xffff0000, v81
	v_pk_fma_f32 v[50:51], v[50:51], 0.5, v[62:63] op_sel_hi:[1,0,1]
	v_pk_fma_f32 v[60:61], v[48:49], 0.5, v[60:61] op_sel_hi:[1,0,1]
	v_mul_f32_e32 v49, v51, v51
	v_mul_f32_e32 v48, v61, v61
	v_fmac_f32_e32 v48, v60, v60
	v_fmac_f32_e32 v49, v50, v50
	v_add_f32_e32 v57, v74, v57
	v_add_f32_e32 v48, v48, v49
	v_add_f32_e32 v48, v57, v48
	v_mov_b32_e32 v49, v48
	s_nop 1
	v_permlane16_swap_b32_e32 v49, v48
	v_cvt_pk_bf16_f32 v52, v52, v53
	v_cvt_pk_bf16_f32 v53, v54, v55
	v_cvt_pk_bf16_f32 v57, v58, v59
	global_store_dwordx2 v[72:73], v[52:53], off offset:256
	s_waitcnt lgkmcnt(0)
	v_add_f32_e32 v48, v48, v49
	v_mov_b32_e32 v49, v48
	s_nop 1
	v_permlane32_swap_b32_e32 v49, v48
	v_cvt_pk_bf16_f32 v52, v60, v61
	v_cvt_pk_bf16_f32 v53, v50, v51
	global_store_dwordx2 v[72:73], v[56:57], off offset:32
	global_store_dwordx2 v[72:73], v[52:53], off offset:288
	s_and_saveexec_b64 s[28:29], s[38:39]
	s_cbranch_execz .LBB0_419
	s_waitcnt lgkmcnt(0)
	v_add_f32_e32 v48, v48, v49
	ds_write_b32 v166, v48
.LBB0_419:
	s_or_b64 exec, exec, s[28:29]
	v_mov_b32_e32 v57, v145
	v_add_u32_e32 v56, 0x4000, v144
	s_waitcnt lgkmcnt(0)
	v_lshl_add_u64 v[48:49], v[56:57], 1, s[60:61]
	global_load_dwordx2 v[54:55], v[48:49], off
	global_load_dwordx2 v[52:53], v[48:49], off offset:32
	global_load_dwordx2 v[50:51], v[48:49], off offset:256
	s_nop 0
	global_load_dwordx2 v[48:49], v[48:49], off offset:288
	s_waitcnt vmcnt(11)
	v_lshlrev_b32_e32 v60, 16, v70
	v_and_b32_e32 v61, 0xffff0000, v70
	v_lshlrev_b32_e32 v62, 16, v71
	v_and_b32_e32 v63, 0xffff0000, v71
	v_pk_fma_f32 v[44:45], v[44:45], 0.5, v[60:61] op_sel_hi:[1,0,1]
	v_pk_fma_f32 v[46:47], v[46:47], 0.5, v[62:63] op_sel_hi:[1,0,1]
	v_mul_f32_e32 v57, v45, v45
	v_lshl_add_u64 v[58:59], v[144:145], 1, s[60:61]
	v_fmac_f32_e32 v57, v44, v44
	v_mul_f32_e32 v60, v47, v47
	v_cvt_pk_bf16_f32 v44, v44, v45
	v_cvt_pk_bf16_f32 v45, v46, v47
	v_fmac_f32_e32 v60, v46, v46
	global_store_dwordx2 v[58:59], v[44:45], off
	s_waitcnt vmcnt(11)
	v_lshlrev_b32_e32 v44, 16, v68
	v_and_b32_e32 v45, 0xffff0000, v68
	v_lshlrev_b32_e32 v46, 16, v69
	v_and_b32_e32 v47, 0xffff0000, v69
	v_pk_fma_f32 v[42:43], v[42:43], 0.5, v[46:47] op_sel_hi:[1,0,1]
	v_pk_fma_f32 v[40:41], v[40:41], 0.5, v[44:45] op_sel_hi:[1,0,1]
	v_mul_f32_e32 v45, v43, v43
	v_mul_f32_e32 v44, v41, v41
	v_fmac_f32_e32 v44, v40, v40
	v_fmac_f32_e32 v45, v42, v42
	v_add_f32_e32 v57, v57, v60
	v_add_f32_e32 v44, v44, v45
	v_add_f32_e32 v57, v57, v44
	s_waitcnt vmcnt(10)
	v_lshlrev_b32_e32 v44, 16, v66
	v_and_b32_e32 v45, 0xffff0000, v66
	v_lshlrev_b32_e32 v46, 16, v67
	v_and_b32_e32 v47, 0xffff0000, v67
	v_pk_fma_f32 v[38:39], v[38:39], 0.5, v[46:47] op_sel_hi:[1,0,1]
	v_pk_fma_f32 v[36:37], v[36:37], 0.5, v[44:45] op_sel_hi:[1,0,1]
	v_cvt_pk_bf16_f32 v40, v40, v41
	v_mul_f32_e32 v41, v37, v37
	v_mul_f32_e32 v44, v39, v39
	v_fmac_f32_e32 v41, v36, v36
	v_fmac_f32_e32 v44, v38, v38
	v_add_f32_e32 v41, v41, v44
	s_waitcnt vmcnt(9)
	v_lshlrev_b32_e32 v44, 16, v64
	v_and_b32_e32 v45, 0xffff0000, v64
	v_lshlrev_b32_e32 v46, 16, v65
	v_and_b32_e32 v47, 0xffff0000, v65
	v_pk_fma_f32 v[34:35], v[34:35], 0.5, v[46:47] op_sel_hi:[1,0,1]
	v_pk_fma_f32 v[44:45], v[32:33], 0.5, v[44:45] op_sel_hi:[1,0,1]
	v_mul_f32_e32 v33, v35, v35
	v_mul_f32_e32 v32, v45, v45
	v_fmac_f32_e32 v32, v44, v44
	v_fmac_f32_e32 v33, v34, v34
	v_add_f32_e32 v41, v57, v41
	v_add_f32_e32 v32, v32, v33
	v_add_f32_e32 v32, v41, v32
	v_mov_b32_e32 v33, v32
	s_nop 1
	v_permlane16_swap_b32_e32 v33, v32
	v_cvt_pk_bf16_f32 v36, v36, v37
	v_cvt_pk_bf16_f32 v37, v38, v39
	v_cvt_pk_bf16_f32 v41, v42, v43
	global_store_dwordx2 v[58:59], v[36:37], off offset:256
	s_waitcnt lgkmcnt(0)
	v_add_f32_e32 v32, v32, v33
	v_mov_b32_e32 v33, v32
	s_nop 1
	v_permlane32_swap_b32_e32 v33, v32
	v_cvt_pk_bf16_f32 v36, v44, v45
	v_cvt_pk_bf16_f32 v37, v34, v35
	global_store_dwordx2 v[58:59], v[40:41], off offset:32
	global_store_dwordx2 v[58:59], v[36:37], off offset:288
	s_and_saveexec_b64 s[28:29], s[38:39]
	s_cbranch_execz .LBB0_421
	s_waitcnt lgkmcnt(0)
	v_add_f32_e32 v32, v32, v33
	ds_write_b32 v167, v32
.LBB0_421:
	s_or_b64 exec, exec, s[28:29]
	s_waitcnt vmcnt(7)
	v_lshlrev_b32_e32 v42, 16, v54
	v_add_u32_e32 v144, 0x4000, v56
	s_waitcnt lgkmcnt(0)
	v_lshl_add_u64 v[32:33], v[144:145], 1, s[60:61]
	global_load_dwordx2 v[38:39], v[32:33], off
	global_load_dwordx2 v[36:37], v[32:33], off offset:32
	global_load_dwordx2 v[34:35], v[32:33], off offset:256
	s_nop 0
	global_load_dwordx2 v[32:33], v[32:33], off offset:288
	v_and_b32_e32 v43, 0xffff0000, v54
	v_lshlrev_b32_e32 v44, 16, v55
	v_and_b32_e32 v45, 0xffff0000, v55
	v_pk_fma_f32 v[28:29], v[28:29], 0.5, v[42:43] op_sel_hi:[1,0,1]
	v_mov_b32_e32 v57, v145
	v_pk_fma_f32 v[30:31], v[30:31], 0.5, v[44:45] op_sel_hi:[1,0,1]
	v_mul_f32_e32 v42, v29, v29
	v_lshl_add_u64 v[40:41], v[56:57], 1, s[60:61]
	v_fmac_f32_e32 v42, v28, v28
	v_mul_f32_e32 v43, v31, v31
	v_cvt_pk_bf16_f32 v28, v28, v29
	v_cvt_pk_bf16_f32 v29, v30, v31
	v_fmac_f32_e32 v43, v30, v30
	global_store_dwordx2 v[40:41], v[28:29], off
	s_waitcnt vmcnt(11)
	v_lshlrev_b32_e32 v28, 16, v52
	v_and_b32_e32 v29, 0xffff0000, v52
	v_lshlrev_b32_e32 v30, 16, v53
	v_and_b32_e32 v31, 0xffff0000, v53
	v_pk_fma_f32 v[26:27], v[26:27], 0.5, v[30:31] op_sel_hi:[1,0,1]
	v_pk_fma_f32 v[24:25], v[24:25], 0.5, v[28:29] op_sel_hi:[1,0,1]
	v_mul_f32_e32 v29, v27, v27
	v_mul_f32_e32 v28, v25, v25
	v_fmac_f32_e32 v28, v24, v24
	v_fmac_f32_e32 v29, v26, v26
	v_add_f32_e32 v42, v42, v43
	v_add_f32_e32 v28, v28, v29
	v_add_f32_e32 v42, v42, v28
	s_waitcnt vmcnt(10)
	v_lshlrev_b32_e32 v28, 16, v50
	v_and_b32_e32 v29, 0xffff0000, v50
	v_lshlrev_b32_e32 v30, 16, v51
	v_and_b32_e32 v31, 0xffff0000, v51
	v_pk_fma_f32 v[22:23], v[22:23], 0.5, v[30:31] op_sel_hi:[1,0,1]
	v_pk_fma_f32 v[20:21], v[20:21], 0.5, v[28:29] op_sel_hi:[1,0,1]
	v_cvt_pk_bf16_f32 v24, v24, v25
	v_mul_f32_e32 v25, v21, v21
	v_mul_f32_e32 v28, v23, v23
	v_fmac_f32_e32 v25, v20, v20
	v_fmac_f32_e32 v28, v22, v22
	v_add_f32_e32 v25, v25, v28
	s_waitcnt vmcnt(9)
	v_lshlrev_b32_e32 v28, 16, v48
	v_and_b32_e32 v29, 0xffff0000, v48
	v_lshlrev_b32_e32 v30, 16, v49
	v_and_b32_e32 v31, 0xffff0000, v49
	v_pk_fma_f32 v[18:19], v[18:19], 0.5, v[30:31] op_sel_hi:[1,0,1]
	v_pk_fma_f32 v[28:29], v[16:17], 0.5, v[28:29] op_sel_hi:[1,0,1]
	v_mul_f32_e32 v17, v19, v19
	v_mul_f32_e32 v16, v29, v29
	v_fmac_f32_e32 v16, v28, v28
	v_fmac_f32_e32 v17, v18, v18
	v_add_f32_e32 v25, v42, v25
	v_add_f32_e32 v16, v16, v17
	v_add_f32_e32 v16, v25, v16
	v_mov_b32_e32 v17, v16
	s_nop 1
	v_permlane16_swap_b32_e32 v17, v16
	v_cvt_pk_bf16_f32 v20, v20, v21
	v_cvt_pk_bf16_f32 v21, v22, v23
	v_cvt_pk_bf16_f32 v25, v26, v27
	global_store_dwordx2 v[40:41], v[20:21], off offset:256
	s_waitcnt lgkmcnt(0)
	v_add_f32_e32 v16, v16, v17
	v_mov_b32_e32 v17, v16
	s_nop 1
	v_permlane32_swap_b32_e32 v17, v16
	v_cvt_pk_bf16_f32 v20, v28, v29
	v_cvt_pk_bf16_f32 v21, v18, v19
	global_store_dwordx2 v[40:41], v[24:25], off offset:32
	global_store_dwordx2 v[40:41], v[20:21], off offset:288
	s_and_saveexec_b64 s[28:29], s[38:39]
	s_cbranch_execz .LBB0_423
	s_waitcnt lgkmcnt(0)
	v_add_f32_e32 v16, v16, v17
	ds_write_b32 v168, v16
.LBB0_423:
	s_or_b64 exec, exec, s[28:29]
	s_waitcnt vmcnt(7)
	v_lshlrev_b32_e32 v16, 16, v38
	s_waitcnt lgkmcnt(0)
	v_and_b32_e32 v17, 0xffff0000, v38
	v_lshlrev_b32_e32 v18, 16, v39
	v_and_b32_e32 v19, 0xffff0000, v39
	v_pk_fma_f32 v[12:13], v[12:13], 0.5, v[16:17] op_sel_hi:[1,0,1]
	v_pk_fma_f32 v[14:15], v[14:15], 0.5, v[18:19] op_sel_hi:[1,0,1]
	v_mul_f32_e32 v16, v13, v13
	v_fmac_f32_e32 v16, v12, v12
	v_lshl_add_u64 v[20:21], v[144:145], 1, s[60:61]
	v_mul_f32_e32 v17, v15, v15
	v_cvt_pk_bf16_f32 v12, v12, v13
	v_cvt_pk_bf16_f32 v13, v14, v15
	v_fmac_f32_e32 v17, v14, v14
	global_store_dwordx2 v[20:21], v[12:13], off
	s_waitcnt vmcnt(7)
	v_lshlrev_b32_e32 v12, 16, v36
	v_and_b32_e32 v13, 0xffff0000, v36
	v_lshlrev_b32_e32 v14, 16, v37
	v_and_b32_e32 v15, 0xffff0000, v37
	v_pk_fma_f32 v[10:11], v[10:11], 0.5, v[14:15] op_sel_hi:[1,0,1]
	v_pk_fma_f32 v[8:9], v[8:9], 0.5, v[12:13] op_sel_hi:[1,0,1]
	v_mul_f32_e32 v13, v11, v11
	v_mul_f32_e32 v12, v9, v9
	v_fmac_f32_e32 v12, v8, v8
	v_fmac_f32_e32 v13, v10, v10
	v_add_f32_e32 v16, v16, v17
	v_add_f32_e32 v12, v12, v13
	v_add_f32_e32 v16, v16, v12
	s_waitcnt vmcnt(6)
	v_lshlrev_b32_e32 v12, 16, v34
	v_and_b32_e32 v13, 0xffff0000, v34
	v_lshlrev_b32_e32 v14, 16, v35
	v_and_b32_e32 v15, 0xffff0000, v35
	v_pk_fma_f32 v[6:7], v[6:7], 0.5, v[14:15] op_sel_hi:[1,0,1]
	v_pk_fma_f32 v[4:5], v[4:5], 0.5, v[12:13] op_sel_hi:[1,0,1]
	v_cvt_pk_bf16_f32 v8, v8, v9
	v_mul_f32_e32 v9, v5, v5
	v_mul_f32_e32 v12, v7, v7
	v_fmac_f32_e32 v9, v4, v4
	v_fmac_f32_e32 v12, v6, v6
	v_add_f32_e32 v9, v9, v12
	s_waitcnt vmcnt(5)
	v_lshlrev_b32_e32 v12, 16, v32
	v_and_b32_e32 v13, 0xffff0000, v32
	v_lshlrev_b32_e32 v14, 16, v33
	v_and_b32_e32 v15, 0xffff0000, v33
	v_pk_fma_f32 v[2:3], v[2:3], 0.5, v[14:15] op_sel_hi:[1,0,1]
	v_pk_fma_f32 v[12:13], v[0:1], 0.5, v[12:13] op_sel_hi:[1,0,1]
	v_mul_f32_e32 v1, v3, v3
	v_mul_f32_e32 v0, v13, v13
	v_fmac_f32_e32 v0, v12, v12
	v_fmac_f32_e32 v1, v2, v2
	v_add_f32_e32 v9, v16, v9
	v_add_f32_e32 v0, v0, v1
	v_add_f32_e32 v0, v9, v0
	v_mov_b32_e32 v1, v0
	s_nop 1
	v_permlane16_swap_b32_e32 v1, v0
	v_cvt_pk_bf16_f32 v4, v4, v5
	v_cvt_pk_bf16_f32 v5, v6, v7
	v_cvt_pk_bf16_f32 v9, v10, v11
	global_store_dwordx2 v[20:21], v[4:5], off offset:256
	s_waitcnt lgkmcnt(0)
	v_add_f32_e32 v0, v0, v1
	v_mov_b32_e32 v1, v0
	s_nop 1
	v_permlane32_swap_b32_e32 v1, v0
	v_cvt_pk_bf16_f32 v4, v12, v13
	v_cvt_pk_bf16_f32 v5, v2, v3
	global_store_dwordx2 v[20:21], v[8:9], off offset:32
	global_store_dwordx2 v[20:21], v[4:5], off offset:288
	s_and_saveexec_b64 s[28:29], s[38:39]
	s_cbranch_execz .LBB0_425
	s_waitcnt lgkmcnt(0)
	v_add_f32_e32 v0, v0, v1
	ds_write_b32 v169, v0

.LBB0_459:
	s_ashr_i32 s53, s52, 31
	s_lshl_b64 s[28:29], s[52:53], 20
	s_add_u32 s60, s2, s28
	s_addc_u32 s61, s3, s29
	v_lshl_add_u32 v144, s50, 8, v167
	v_lshl_add_u64 v[128:129], v[144:145], 2, s[60:61]
	global_load_dwordx4 v[204:207], v[128:129], off
	global_load_dwordx4 v[208:211], v[128:129], off offset:64
	global_load_dwordx4 v[212:215], v[128:129], off offset:512
	global_load_dwordx4 v[216:219], v[128:129], off offset:576
	v_mov_b32_e32 v165, v145
	v_add_u32_e32 v164, 0x4000, v144
	v_lshl_add_u64 v[128:129], v[164:165], 2, s[60:61]
	global_load_dwordx4 v[140:143], v[128:129], off
	global_load_dwordx4 v[136:139], v[128:129], off offset:64
	global_load_dwordx4 v[132:135], v[128:129], off offset:512
	s_nop 0
	global_load_dwordx4 v[128:131], v[128:129], off offset:576
	v_and_b32_e32 v178, 64, v183
	v_xor_b32_e32 v165, 16, v183
	v_add_u32_e32 v178, 64, v178
	s_lshl_b64 s[28:29], s[52:53], 19
	v_xor_b32_e32 v179, 32, v183
	v_cmp_lt_i32_e32 vcc, v165, v178
	s_add_u32 s58, s0, s28
	s_addc_u32 s59, s1, s29
	v_cndmask_b32_e32 v165, v183, v165, vcc
	v_cmp_lt_i32_e32 vcc, v179, v178
	v_lshl_add_u64 v[180:181], v[144:145], 1, s[58:59]
	s_waitcnt vmcnt(0)
	v_pk_fma_f32 v[126:127], v[126:127], 0.5, v[206:207] op_sel_hi:[1,0,1]
	v_pk_fma_f32 v[124:125], v[124:125], 0.5, v[204:205] op_sel_hi:[1,0,1]
	v_pk_fma_f32 v[122:123], v[122:123], 0.5, v[210:211] op_sel_hi:[1,0,1]
	v_pk_fma_f32 v[120:121], v[120:121], 0.5, v[208:209] op_sel_hi:[1,0,1]
	v_cndmask_b32_e32 v178, v183, v179, vcc
	v_lshlrev_b32_e32 v179, 2, v165
	v_pk_fma_f32 v[118:119], v[118:119], 0.5, v[214:215] op_sel_hi:[1,0,1]
	v_pk_fma_f32 v[116:117], v[116:117], 0.5, v[212:213] op_sel_hi:[1,0,1]
	v_pk_fma_f32 v[202:203], v[112:113], 0.5, v[216:217] op_sel_hi:[1,0,1]
	v_mul_f32_e32 v144, v125, v125
	v_mul_f32_e32 v165, v127, v127
	v_cvt_pk_bf16_f32 v112, v124, v125
	v_cvt_pk_bf16_f32 v113, v126, v127
	v_mul_f32_e32 v125, v121, v121
	v_mul_f32_e32 v127, v123, v123
	v_pk_fma_f32 v[114:115], v[114:115], 0.5, v[218:219] op_sel_hi:[1,0,1]
	v_cvt_pk_bf16_f32 v204, v120, v121
	v_mul_f32_e32 v121, v117, v117
	v_mul_f32_e32 v205, v119, v119
	v_fmac_f32_e32 v144, v124, v124
	v_fmac_f32_e32 v165, v126, v126
	v_fmac_f32_e32 v125, v120, v120
	v_fmac_f32_e32 v127, v122, v122
	v_mul_f32_e32 v206, v203, v203
	v_mul_f32_e32 v207, v115, v115
	global_store_dwordx2 v[180:181], v[112:113], off
	v_fmac_f32_e32 v121, v116, v116
	v_fmac_f32_e32 v205, v118, v118
	v_add_f32_e32 v112, v144, v165
	v_add_f32_e32 v113, v125, v127
	v_fmac_f32_e32 v206, v202, v202
	v_fmac_f32_e32 v207, v114, v114
	v_add_f32_e32 v120, v121, v205
	v_add_f32_e32 v112, v112, v113
	v_add_f32_e32 v112, v112, v120
	v_add_f32_e32 v113, v206, v207
	v_add_f32_e32 v112, v112, v113
	v_mov_b32_e32 v113, v112
	s_nop 1
	v_permlane16_swap_b32_e32 v113, v112
	v_lshlrev_b32_e32 v178, 2, v178
	v_cvt_pk_bf16_f32 v116, v116, v117
	v_cvt_pk_bf16_f32 v117, v118, v119
	v_cvt_pk_bf16_f32 v205, v122, v123
	s_waitcnt lgkmcnt(0)
	v_add_f32_e32 v112, v112, v113
	v_mov_b32_e32 v113, v112
	s_nop 1
	v_permlane32_swap_b32_e32 v113, v112
	global_store_dwordx2 v[180:181], v[116:117], off offset:256
	v_cvt_pk_bf16_f32 v116, v202, v203
	v_cvt_pk_bf16_f32 v117, v114, v115
	global_store_dwordx2 v[180:181], v[204:205], off offset:32
	global_store_dwordx2 v[180:181], v[116:117], off offset:288
	s_and_saveexec_b64 s[28:29], s[38:39]
	s_cbranch_execz .LBB0_461
	s_waitcnt lgkmcnt(0)
	v_add_f32_e32 v112, v112, v113
	ds_write_b32 v168, v112
.LBB0_461:
	s_or_b64 exec, exec, s[28:29]
	v_pk_fma_f32 v[108:109], v[108:109], 0.5, v[140:141] op_sel_hi:[1,0,1]
	v_add_u32_e32 v144, 0x4000, v164
	s_waitcnt lgkmcnt(0)
	v_lshl_add_u64 v[112:113], v[144:145], 2, s[60:61]
	global_load_dwordx4 v[124:127], v[112:113], off
	global_load_dwordx4 v[120:123], v[112:113], off offset:64
	global_load_dwordx4 v[116:119], v[112:113], off offset:512
	s_nop 0
	global_load_dwordx4 v[112:115], v[112:113], off offset:576
	v_mov_b32_e32 v165, v145
	v_pk_fma_f32 v[110:111], v[110:111], 0.5, v[142:143] op_sel_hi:[1,0,1]
	v_mul_f32_e32 v140, v109, v109
	v_lshl_add_u64 v[164:165], v[164:165], 1, s[58:59]
	v_fmac_f32_e32 v140, v108, v108
	v_cvt_pk_bf16_f32 v108, v108, v109
	v_cvt_pk_bf16_f32 v109, v110, v111
	v_pk_fma_f32 v[106:107], v[106:107], 0.5, v[138:139] op_sel_hi:[1,0,1]
	v_pk_fma_f32 v[104:105], v[104:105], 0.5, v[136:137] op_sel_hi:[1,0,1]
	global_store_dwordx2 v[164:165], v[108:109], off
	v_mul_f32_e32 v108, v105, v105
	v_mul_f32_e32 v109, v107, v107
	v_mul_f32_e32 v141, v111, v111
	v_fmac_f32_e32 v108, v104, v104
	v_fmac_f32_e32 v109, v106, v106
	v_pk_fma_f32 v[102:103], v[102:103], 0.5, v[134:135] op_sel_hi:[1,0,1]
	v_pk_fma_f32 v[100:101], v[100:101], 0.5, v[132:133] op_sel_hi:[1,0,1]
	v_fmac_f32_e32 v141, v110, v110
	v_add_f32_e32 v108, v108, v109
	v_cvt_pk_bf16_f32 v104, v104, v105
	v_mul_f32_e32 v105, v101, v101
	v_mul_f32_e32 v109, v103, v103
	v_add_f32_e32 v140, v140, v141
	v_fmac_f32_e32 v105, v100, v100
	v_fmac_f32_e32 v109, v102, v102
	v_add_f32_e32 v108, v140, v108
	v_add_f32_e32 v105, v105, v109
	v_add_f32_e32 v105, v108, v105
	v_pk_fma_f32 v[98:99], v[98:99], 0.5, v[130:131] op_sel_hi:[1,0,1]
	v_pk_fma_f32 v[108:109], v[96:97], 0.5, v[128:129] op_sel_hi:[1,0,1]
	v_mul_f32_e32 v97, v99, v99
	v_mul_f32_e32 v96, v109, v109
	v_fmac_f32_e32 v96, v108, v108
	v_fmac_f32_e32 v97, v98, v98
	v_add_f32_e32 v96, v96, v97
	v_add_f32_e32 v96, v105, v96
	v_mov_b32_e32 v97, v96
	s_nop 1
	v_permlane16_swap_b32_e32 v97, v96
	v_cvt_pk_bf16_f32 v100, v100, v101
	v_cvt_pk_bf16_f32 v101, v102, v103
	v_cvt_pk_bf16_f32 v105, v106, v107
	global_store_dwordx2 v[164:165], v[100:101], off offset:256
	s_waitcnt lgkmcnt(0)
	v_add_f32_e32 v96, v96, v97
	v_mov_b32_e32 v97, v96
	s_nop 1
	v_permlane32_swap_b32_e32 v97, v96
	v_cvt_pk_bf16_f32 v100, v108, v109
	v_cvt_pk_bf16_f32 v101, v98, v99
	global_store_dwordx2 v[164:165], v[104:105], off offset:32
	global_store_dwordx2 v[164:165], v[100:101], off offset:288
	s_and_saveexec_b64 s[28:29], s[38:39]
	s_cbranch_execz .LBB0_463
	s_waitcnt lgkmcnt(0)
	v_add_f32_e32 v96, v96, v97
	ds_write_b32 v169, v96
.LBB0_463:
	s_or_b64 exec, exec, s[28:29]
	v_mov_b32_e32 v129, v145
	v_add_u32_e32 v128, 0x4000, v144
	s_waitcnt lgkmcnt(0)
	v_lshl_add_u64 v[96:97], v[128:129], 2, s[60:61]
	global_load_dwordx4 v[108:111], v[96:97], off
	global_load_dwordx4 v[104:107], v[96:97], off offset:64
	global_load_dwordx4 v[100:103], v[96:97], off offset:512
	s_nop 0
	global_load_dwordx4 v[96:99], v[96:97], off offset:576
	s_waitcnt vmcnt(11)
	v_pk_fma_f32 v[92:93], v[92:93], 0.5, v[124:125] op_sel_hi:[1,0,1]
	v_pk_fma_f32 v[94:95], v[94:95], 0.5, v[126:127] op_sel_hi:[1,0,1]
	v_mul_f32_e32 v124, v93, v93
	v_lshl_add_u64 v[130:131], v[144:145], 1, s[58:59]
	v_fmac_f32_e32 v124, v92, v92
	v_cvt_pk_bf16_f32 v92, v92, v93
	v_cvt_pk_bf16_f32 v93, v94, v95
	s_waitcnt vmcnt(10)
	v_pk_fma_f32 v[90:91], v[90:91], 0.5, v[122:123] op_sel_hi:[1,0,1]
	v_pk_fma_f32 v[88:89], v[88:89], 0.5, v[120:121] op_sel_hi:[1,0,1]
	global_store_dwordx2 v[130:131], v[92:93], off
	v_mul_f32_e32 v92, v89, v89
	v_mul_f32_e32 v93, v91, v91
	v_mul_f32_e32 v125, v95, v95
	v_fmac_f32_e32 v92, v88, v88
	v_fmac_f32_e32 v93, v90, v90
	s_waitcnt vmcnt(10)
	v_pk_fma_f32 v[86:87], v[86:87], 0.5, v[118:119] op_sel_hi:[1,0,1]
	v_pk_fma_f32 v[84:85], v[84:85], 0.5, v[116:117] op_sel_hi:[1,0,1]
	v_fmac_f32_e32 v125, v94, v94
	v_add_f32_e32 v92, v92, v93
	v_cvt_pk_bf16_f32 v88, v88, v89
	v_mul_f32_e32 v89, v85, v85
	v_mul_f32_e32 v93, v87, v87
	v_add_f32_e32 v124, v124, v125
	v_fmac_f32_e32 v89, v84, v84
	v_fmac_f32_e32 v93, v86, v86
	v_add_f32_e32 v92, v124, v92
	v_add_f32_e32 v89, v89, v93
	v_add_f32_e32 v89, v92, v89
	s_waitcnt vmcnt(9)
	v_pk_fma_f32 v[82:83], v[82:83], 0.5, v[114:115] op_sel_hi:[1,0,1]
	v_pk_fma_f32 v[92:93], v[80:81], 0.5, v[112:113] op_sel_hi:[1,0,1]
	v_mul_f32_e32 v81, v83, v83
	v_mul_f32_e32 v80, v93, v93
	v_fmac_f32_e32 v80, v92, v92
	v_fmac_f32_e32 v81, v82, v82
	v_add_f32_e32 v80, v80, v81
	v_add_f32_e32 v80, v89, v80
	v_mov_b32_e32 v81, v80
	s_nop 1
	v_permlane16_swap_b32_e32 v81, v80
	v_cvt_pk_bf16_f32 v84, v84, v85
	v_cvt_pk_bf16_f32 v85, v86, v87
	v_cvt_pk_bf16_f32 v89, v90, v91
	global_store_dwordx2 v[130:131], v[84:85], off offset:256
	s_waitcnt lgkmcnt(0)
	v_add_f32_e32 v80, v80, v81
	v_mov_b32_e32 v81, v80
	s_nop 1
	v_permlane32_swap_b32_e32 v81, v80
	v_cvt_pk_bf16_f32 v84, v92, v93
	v_cvt_pk_bf16_f32 v85, v82, v83
	global_store_dwordx2 v[130:131], v[88:89], off offset:32
	global_store_dwordx2 v[130:131], v[84:85], off offset:288
	s_and_saveexec_b64 s[28:29], s[38:39]
	s_cbranch_execz .LBB0_465
	s_waitcnt lgkmcnt(0)
	v_add_f32_e32 v80, v80, v81
	ds_write_b32 v170, v80
.LBB0_465:
	s_or_b64 exec, exec, s[28:29]
	s_waitcnt vmcnt(7)
	v_pk_fma_f32 v[76:77], v[76:77], 0.5, v[108:109] op_sel_hi:[1,0,1]
	v_add_u32_e32 v144, 0x14000, v128
	s_waitcnt lgkmcnt(0)
	v_lshl_add_u64 v[80:81], v[144:145], 2, s[60:61]
	global_load_dwordx4 v[92:95], v[80:81], off
	global_load_dwordx4 v[88:91], v[80:81], off offset:64
	global_load_dwordx4 v[84:87], v[80:81], off offset:512
	s_nop 0
	global_load_dwordx4 v[80:83], v[80:81], off offset:576
	v_mov_b32_e32 v129, v145
	v_pk_fma_f32 v[78:79], v[78:79], 0.5, v[110:111] op_sel_hi:[1,0,1]
	v_mul_f32_e32 v108, v77, v77
	v_lshl_add_u64 v[112:113], v[128:129], 1, s[58:59]
	v_fmac_f32_e32 v108, v76, v76
	v_cvt_pk_bf16_f32 v76, v76, v77
	v_cvt_pk_bf16_f32 v77, v78, v79
	s_waitcnt vmcnt(10)
	v_pk_fma_f32 v[74:75], v[74:75], 0.5, v[106:107] op_sel_hi:[1,0,1]
	v_pk_fma_f32 v[72:73], v[72:73], 0.5, v[104:105] op_sel_hi:[1,0,1]
	global_store_dwordx2 v[112:113], v[76:77], off
	v_mul_f32_e32 v76, v73, v73
	v_mul_f32_e32 v77, v75, v75
	v_mul_f32_e32 v109, v79, v79
	v_fmac_f32_e32 v76, v72, v72
	v_fmac_f32_e32 v77, v74, v74
	s_waitcnt vmcnt(10)
	v_pk_fma_f32 v[70:71], v[70:71], 0.5, v[102:103] op_sel_hi:[1,0,1]
	v_pk_fma_f32 v[68:69], v[68:69], 0.5, v[100:101] op_sel_hi:[1,0,1]
	v_fmac_f32_e32 v109, v78, v78
	v_add_f32_e32 v76, v76, v77
	v_cvt_pk_bf16_f32 v72, v72, v73
	v_mul_f32_e32 v73, v69, v69
	v_mul_f32_e32 v77, v71, v71
	v_add_f32_e32 v108, v108, v109
	v_fmac_f32_e32 v73, v68, v68
	v_fmac_f32_e32 v77, v70, v70
	v_add_f32_e32 v76, v108, v76
	v_add_f32_e32 v73, v73, v77
	v_add_f32_e32 v73, v76, v73
	s_waitcnt vmcnt(9)
	v_pk_fma_f32 v[66:67], v[66:67], 0.5, v[98:99] op_sel_hi:[1,0,1]
	v_pk_fma_f32 v[76:77], v[64:65], 0.5, v[96:97] op_sel_hi:[1,0,1]
	v_mul_f32_e32 v65, v67, v67
	v_mul_f32_e32 v64, v77, v77
	v_fmac_f32_e32 v64, v76, v76
	v_fmac_f32_e32 v65, v66, v66
	v_add_f32_e32 v64, v64, v65
	v_add_f32_e32 v64, v73, v64
	v_mov_b32_e32 v65, v64
	s_nop 1
	v_permlane16_swap_b32_e32 v65, v64
	v_cvt_pk_bf16_f32 v68, v68, v69
	v_cvt_pk_bf16_f32 v69, v70, v71
	v_cvt_pk_bf16_f32 v73, v74, v75
	global_store_dwordx2 v[112:113], v[68:69], off offset:256
	s_waitcnt lgkmcnt(0)
	v_add_f32_e32 v64, v64, v65
	v_mov_b32_e32 v65, v64
	s_nop 1
	v_permlane32_swap_b32_e32 v65, v64
	v_cvt_pk_bf16_f32 v68, v76, v77
	v_cvt_pk_bf16_f32 v69, v66, v67
	global_store_dwordx2 v[112:113], v[72:73], off offset:32
	global_store_dwordx2 v[112:113], v[68:69], off offset:288
	s_and_saveexec_b64 s[28:29], s[38:39]
	s_cbranch_execz .LBB0_467
	s_waitcnt lgkmcnt(0)
	v_add_f32_e32 v64, v64, v65
	ds_write_b32 v171, v64
.LBB0_467:
	s_or_b64 exec, exec, s[28:29]
	v_mov_b32_e32 v97, v145
	v_add_u32_e32 v96, 0x4000, v144
	s_waitcnt lgkmcnt(0)
	v_lshl_add_u64 v[64:65], v[96:97], 2, s[60:61]
	global_load_dwordx4 v[76:79], v[64:65], off
	global_load_dwordx4 v[72:75], v[64:65], off offset:64
	global_load_dwordx4 v[68:71], v[64:65], off offset:512
	s_nop 0
	global_load_dwordx4 v[64:67], v[64:65], off offset:576
	s_waitcnt vmcnt(11)
	v_pk_fma_f32 v[60:61], v[60:61], 0.5, v[92:93] op_sel_hi:[1,0,1]
	v_pk_fma_f32 v[62:63], v[62:63], 0.5, v[94:95] op_sel_hi:[1,0,1]
	v_mul_f32_e32 v92, v61, v61
	v_lshl_add_u64 v[98:99], v[144:145], 1, s[58:59]
	v_fmac_f32_e32 v92, v60, v60
	v_cvt_pk_bf16_f32 v60, v60, v61
	v_cvt_pk_bf16_f32 v61, v62, v63
	s_waitcnt vmcnt(10)
	v_pk_fma_f32 v[58:59], v[58:59], 0.5, v[90:91] op_sel_hi:[1,0,1]
	v_pk_fma_f32 v[56:57], v[56:57], 0.5, v[88:89] op_sel_hi:[1,0,1]
	global_store_dwordx2 v[98:99], v[60:61], off
	v_mul_f32_e32 v60, v57, v57
	v_mul_f32_e32 v61, v59, v59
	v_mul_f32_e32 v93, v63, v63
	v_fmac_f32_e32 v60, v56, v56
	v_fmac_f32_e32 v61, v58, v58
	s_waitcnt vmcnt(10)
	v_pk_fma_f32 v[54:55], v[54:55], 0.5, v[86:87] op_sel_hi:[1,0,1]
	v_pk_fma_f32 v[52:53], v[52:53], 0.5, v[84:85] op_sel_hi:[1,0,1]
	v_fmac_f32_e32 v93, v62, v62
	v_add_f32_e32 v60, v60, v61
	v_cvt_pk_bf16_f32 v56, v56, v57
	v_mul_f32_e32 v57, v53, v53
	v_mul_f32_e32 v61, v55, v55
	v_add_f32_e32 v92, v92, v93
	v_fmac_f32_e32 v57, v52, v52
	v_fmac_f32_e32 v61, v54, v54
	v_add_f32_e32 v60, v92, v60
	v_add_f32_e32 v57, v57, v61
	v_add_f32_e32 v57, v60, v57
	s_waitcnt vmcnt(9)
	v_pk_fma_f32 v[50:51], v[50:51], 0.5, v[82:83] op_sel_hi:[1,0,1]
	v_pk_fma_f32 v[60:61], v[48:49], 0.5, v[80:81] op_sel_hi:[1,0,1]
	v_mul_f32_e32 v49, v51, v51
	v_mul_f32_e32 v48, v61, v61
	v_fmac_f32_e32 v48, v60, v60
	v_fmac_f32_e32 v49, v50, v50
	v_add_f32_e32 v48, v48, v49
	v_add_f32_e32 v48, v57, v48
	v_mov_b32_e32 v49, v48
	s_nop 1
	v_permlane16_swap_b32_e32 v49, v48
	v_cvt_pk_bf16_f32 v52, v52, v53
	v_cvt_pk_bf16_f32 v53, v54, v55
	v_cvt_pk_bf16_f32 v57, v58, v59
	global_store_dwordx2 v[98:99], v[52:53], off offset:256
	s_waitcnt lgkmcnt(0)
	v_add_f32_e32 v48, v48, v49
	v_mov_b32_e32 v49, v48
	s_nop 1
	v_permlane32_swap_b32_e32 v49, v48
	v_cvt_pk_bf16_f32 v52, v60, v61
	v_cvt_pk_bf16_f32 v53, v50, v51
	global_store_dwordx2 v[98:99], v[56:57], off offset:32
	global_store_dwordx2 v[98:99], v[52:53], off offset:288
	s_and_saveexec_b64 s[28:29], s[38:39]
	s_cbranch_execz .LBB0_469
	s_waitcnt lgkmcnt(0)
	v_add_f32_e32 v48, v48, v49
	ds_write_b32 v172, v48
.LBB0_469:
	s_or_b64 exec, exec, s[28:29]
	s_waitcnt vmcnt(7)
	v_pk_fma_f32 v[44:45], v[44:45], 0.5, v[76:77] op_sel_hi:[1,0,1]
	v_add_u32_e32 v144, 0x4000, v96
	s_waitcnt lgkmcnt(0)
	v_lshl_add_u64 v[48:49], v[144:145], 2, s[60:61]
	global_load_dwordx4 v[60:63], v[48:49], off
	global_load_dwordx4 v[56:59], v[48:49], off offset:64
	global_load_dwordx4 v[52:55], v[48:49], off offset:512
	s_nop 0
	global_load_dwordx4 v[48:51], v[48:49], off offset:576
	v_mov_b32_e32 v97, v145
	v_pk_fma_f32 v[46:47], v[46:47], 0.5, v[78:79] op_sel_hi:[1,0,1]
	v_mul_f32_e32 v76, v45, v45
	v_lshl_add_u64 v[80:81], v[96:97], 1, s[58:59]
	v_fmac_f32_e32 v76, v44, v44
	v_cvt_pk_bf16_f32 v44, v44, v45
	v_cvt_pk_bf16_f32 v45, v46, v47
	s_waitcnt vmcnt(10)
	v_pk_fma_f32 v[42:43], v[42:43], 0.5, v[74:75] op_sel_hi:[1,0,1]
	v_pk_fma_f32 v[40:41], v[40:41], 0.5, v[72:73] op_sel_hi:[1,0,1]
	global_store_dwordx2 v[80:81], v[44:45], off
	v_mul_f32_e32 v44, v41, v41
	v_mul_f32_e32 v45, v43, v43
	v_mul_f32_e32 v77, v47, v47
	v_fmac_f32_e32 v44, v40, v40
	v_fmac_f32_e32 v45, v42, v42
	s_waitcnt vmcnt(10)
	v_pk_fma_f32 v[38:39], v[38:39], 0.5, v[70:71] op_sel_hi:[1,0,1]
	v_pk_fma_f32 v[36:37], v[36:37], 0.5, v[68:69] op_sel_hi:[1,0,1]
	v_fmac_f32_e32 v77, v46, v46
	v_add_f32_e32 v44, v44, v45
	v_cvt_pk_bf16_f32 v40, v40, v41
	v_mul_f32_e32 v41, v37, v37
	v_mul_f32_e32 v45, v39, v39
	v_add_f32_e32 v76, v76, v77
	v_fmac_f32_e32 v41, v36, v36
	v_fmac_f32_e32 v45, v38, v38
	v_add_f32_e32 v44, v76, v44
	v_add_f32_e32 v41, v41, v45
	v_add_f32_e32 v41, v44, v41
	s_waitcnt vmcnt(9)
	v_pk_fma_f32 v[34:35], v[34:35], 0.5, v[66:67] op_sel_hi:[1,0,1]
	v_pk_fma_f32 v[44:45], v[32:33], 0.5, v[64:65] op_sel_hi:[1,0,1]
	v_mul_f32_e32 v33, v35, v35
	v_mul_f32_e32 v32, v45, v45
	v_fmac_f32_e32 v32, v44, v44
	v_fmac_f32_e32 v33, v34, v34
	v_add_f32_e32 v32, v32, v33
	v_add_f32_e32 v32, v41, v32
	v_mov_b32_e32 v33, v32
	s_nop 1
	v_permlane16_swap_b32_e32 v33, v32
	v_cvt_pk_bf16_f32 v36, v36, v37
	v_cvt_pk_bf16_f32 v37, v38, v39
	v_cvt_pk_bf16_f32 v41, v42, v43
	global_store_dwordx2 v[80:81], v[36:37], off offset:256
	s_waitcnt lgkmcnt(0)
	v_add_f32_e32 v32, v32, v33
	v_mov_b32_e32 v33, v32
	s_nop 1
	v_permlane32_swap_b32_e32 v33, v32
	v_cvt_pk_bf16_f32 v36, v44, v45
	v_cvt_pk_bf16_f32 v37, v34, v35
	global_store_dwordx2 v[80:81], v[40:41], off offset:32
	global_store_dwordx2 v[80:81], v[36:37], off offset:288
	s_and_saveexec_b64 s[28:29], s[38:39]
	s_cbranch_execz .LBB0_471
	s_waitcnt lgkmcnt(0)
	v_add_f32_e32 v32, v32, v33
	ds_write_b32 v173, v32
.LBB0_471:
	s_or_b64 exec, exec, s[28:29]
	v_mov_b32_e32 v65, v145
	v_add_u32_e32 v64, 0x4000, v144
	s_waitcnt lgkmcnt(0)
	v_lshl_add_u64 v[32:33], v[64:65], 2, s[60:61]
	global_load_dwordx4 v[44:47], v[32:33], off
	global_load_dwordx4 v[40:43], v[32:33], off offset:64
	global_load_dwordx4 v[36:39], v[32:33], off offset:512
	s_nop 0
	global_load_dwordx4 v[32:35], v[32:33], off offset:576
	s_waitcnt vmcnt(11)
	v_pk_fma_f32 v[28:29], v[28:29], 0.5, v[60:61] op_sel_hi:[1,0,1]
	v_pk_fma_f32 v[30:31], v[30:31], 0.5, v[62:63] op_sel_hi:[1,0,1]
	v_mul_f32_e32 v60, v29, v29
	v_lshl_add_u64 v[66:67], v[144:145], 1, s[58:59]
	v_fmac_f32_e32 v60, v28, v28
	v_cvt_pk_bf16_f32 v28, v28, v29
	v_cvt_pk_bf16_f32 v29, v30, v31
	s_waitcnt vmcnt(10)
	v_pk_fma_f32 v[26:27], v[26:27], 0.5, v[58:59] op_sel_hi:[1,0,1]
	v_pk_fma_f32 v[24:25], v[24:25], 0.5, v[56:57] op_sel_hi:[1,0,1]
	global_store_dwordx2 v[66:67], v[28:29], off
	v_mul_f32_e32 v28, v25, v25
	v_mul_f32_e32 v29, v27, v27
	v_mul_f32_e32 v61, v31, v31
	v_fmac_f32_e32 v28, v24, v24
	v_fmac_f32_e32 v29, v26, v26
	s_waitcnt vmcnt(10)
	v_pk_fma_f32 v[22:23], v[22:23], 0.5, v[54:55] op_sel_hi:[1,0,1]
	v_pk_fma_f32 v[20:21], v[20:21], 0.5, v[52:53] op_sel_hi:[1,0,1]
	v_fmac_f32_e32 v61, v30, v30
	v_add_f32_e32 v28, v28, v29
	v_cvt_pk_bf16_f32 v24, v24, v25
	v_mul_f32_e32 v25, v21, v21
	v_mul_f32_e32 v29, v23, v23
	v_add_f32_e32 v60, v60, v61
	v_fmac_f32_e32 v25, v20, v20
	v_fmac_f32_e32 v29, v22, v22
	v_add_f32_e32 v28, v60, v28
	v_add_f32_e32 v25, v25, v29
	v_add_f32_e32 v25, v28, v25
	s_waitcnt vmcnt(9)
	v_pk_fma_f32 v[18:19], v[18:19], 0.5, v[50:51] op_sel_hi:[1,0,1]
	v_pk_fma_f32 v[28:29], v[16:17], 0.5, v[48:49] op_sel_hi:[1,0,1]
	v_mul_f32_e32 v17, v19, v19
	v_mul_f32_e32 v16, v29, v29
	v_fmac_f32_e32 v16, v28, v28
	v_fmac_f32_e32 v17, v18, v18
	v_add_f32_e32 v16, v16, v17
	v_add_f32_e32 v16, v25, v16
	v_mov_b32_e32 v17, v16
	s_nop 1
	v_permlane16_swap_b32_e32 v17, v16
	v_cvt_pk_bf16_f32 v20, v20, v21
	v_cvt_pk_bf16_f32 v21, v22, v23
	v_cvt_pk_bf16_f32 v25, v26, v27
	global_store_dwordx2 v[66:67], v[20:21], off offset:256
	s_waitcnt lgkmcnt(0)
	v_add_f32_e32 v16, v16, v17
	v_mov_b32_e32 v17, v16
	s_nop 1
	v_permlane32_swap_b32_e32 v17, v16
	v_cvt_pk_bf16_f32 v20, v28, v29
	v_cvt_pk_bf16_f32 v21, v18, v19
	global_store_dwordx2 v[66:67], v[24:25], off offset:32
	global_store_dwordx2 v[66:67], v[20:21], off offset:288
	s_and_saveexec_b64 s[28:29], s[38:39]
	s_cbranch_execz .LBB0_473
	s_waitcnt lgkmcnt(0)
	v_add_f32_e32 v16, v16, v17
	ds_write_b32 v174, v16
.LBB0_473:
	s_or_b64 exec, exec, s[28:29]
	s_waitcnt vmcnt(7)
	v_pk_fma_f32 v[12:13], v[12:13], 0.5, v[44:45] op_sel_hi:[1,0,1]
	v_mov_b32_e32 v65, v145
	v_pk_fma_f32 v[14:15], v[14:15], 0.5, v[46:47] op_sel_hi:[1,0,1]
	v_mul_f32_e32 v18, v13, v13
	v_fmac_f32_e32 v18, v12, v12
	s_waitcnt lgkmcnt(0)
	v_lshl_add_u64 v[16:17], v[64:65], 1, s[58:59]
	v_cvt_pk_bf16_f32 v12, v12, v13
	v_cvt_pk_bf16_f32 v13, v14, v15
	s_waitcnt vmcnt(6)
	v_pk_fma_f32 v[10:11], v[10:11], 0.5, v[42:43] op_sel_hi:[1,0,1]
	v_pk_fma_f32 v[8:9], v[8:9], 0.5, v[40:41] op_sel_hi:[1,0,1]
	global_store_dwordx2 v[16:17], v[12:13], off
	v_mul_f32_e32 v12, v9, v9
	v_mul_f32_e32 v13, v11, v11
	v_mul_f32_e32 v19, v15, v15
	v_fmac_f32_e32 v12, v8, v8
	v_fmac_f32_e32 v13, v10, v10
	s_waitcnt vmcnt(6)
	v_pk_fma_f32 v[6:7], v[6:7], 0.5, v[38:39] op_sel_hi:[1,0,1]
	v_pk_fma_f32 v[4:5], v[4:5], 0.5, v[36:37] op_sel_hi:[1,0,1]
	v_fmac_f32_e32 v19, v14, v14
	v_add_f32_e32 v12, v12, v13
	v_cvt_pk_bf16_f32 v8, v8, v9
	v_mul_f32_e32 v9, v5, v5
	v_mul_f32_e32 v13, v7, v7
	v_add_f32_e32 v18, v18, v19
	v_fmac_f32_e32 v9, v4, v4
	v_fmac_f32_e32 v13, v6, v6
	v_add_f32_e32 v12, v18, v12
	v_add_f32_e32 v9, v9, v13
	v_add_f32_e32 v9, v12, v9
	s_waitcnt vmcnt(5)
	v_pk_fma_f32 v[2:3], v[2:3], 0.5, v[34:35] op_sel_hi:[1,0,1]
	v_pk_fma_f32 v[12:13], v[0:1], 0.5, v[32:33] op_sel_hi:[1,0,1]
	v_mul_f32_e32 v1, v3, v3
	v_mul_f32_e32 v0, v13, v13
	v_fmac_f32_e32 v0, v12, v12
	v_fmac_f32_e32 v1, v2, v2
	v_add_f32_e32 v0, v0, v1
	v_add_f32_e32 v0, v9, v0
	v_mov_b32_e32 v1, v0
	s_nop 1
	v_permlane16_swap_b32_e32 v1, v0
	v_cvt_pk_bf16_f32 v4, v4, v5
	v_cvt_pk_bf16_f32 v5, v6, v7
	v_cvt_pk_bf16_f32 v9, v10, v11
	global_store_dwordx2 v[16:17], v[4:5], off offset:256
	s_waitcnt lgkmcnt(0)
	v_add_f32_e32 v0, v0, v1
	v_mov_b32_e32 v1, v0
	s_nop 1
	v_permlane32_swap_b32_e32 v1, v0
	v_cvt_pk_bf16_f32 v4, v12, v13
	v_cvt_pk_bf16_f32 v5, v2, v3
	global_store_dwordx2 v[16:17], v[8:9], off offset:32
	global_store_dwordx2 v[16:17], v[4:5], off offset:288
	s_and_saveexec_b64 s[28:29], s[38:39]
	s_cbranch_execz .LBB0_475
	s_waitcnt lgkmcnt(0)
	v_add_f32_e32 v0, v0, v1
	ds_write_b32 v175, v0

.LBB0_1210:
	s_ashr_i32 s45, s44, 31
	s_lshl_b64 s[4:5], s[44:45], 19
	s_add_u32 s60, s0, s4
	s_addc_u32 s61, s1, s5
	v_lshl_add_u32 v144, s2, 8, v161
	v_lshl_add_u64 v[156:157], v[144:145], 1, s[60:61]
	global_load_dwordx2 v[174:175], v[156:157], off
	global_load_dwordx2 v[176:177], v[156:157], off offset:32
	global_load_dwordx2 v[178:179], v[156:157], off offset:256
	global_load_dwordx2 v[158:159], v[156:157], off offset:288
	v_and_b32_e32 v139, 64, v183
	v_xor_b32_e32 v138, 16, v183
	v_add_u32_e32 v139, 64, v139
	v_cmp_lt_i32_e32 vcc, v138, v139
	v_add_u32_e32 v144, 0x4000, v144
	s_waitcnt vmcnt(0)
	v_lshlrev_b32_e32 v180, 16, v174
	v_cndmask_b32_e32 v138, v183, v138, vcc
	v_lshlrev_b32_e32 v173, 2, v138
	v_xor_b32_e32 v138, 32, v183
	v_cmp_lt_i32_e32 vcc, v138, v139
	v_and_b32_e32 v181, 0xffff0000, v174
	v_lshlrev_b32_e32 v174, 16, v175
	v_cndmask_b32_e32 v138, v183, v138, vcc
	v_lshlrev_b32_e32 v172, 2, v138
	v_lshl_add_u64 v[138:139], v[144:145], 1, s[60:61]
	global_load_dwordx2 v[154:155], v[138:139], off
	global_load_dwordx2 v[142:143], v[138:139], off offset:32
	global_load_dwordx2 v[140:141], v[138:139], off offset:256
	s_nop 0
	global_load_dwordx2 v[138:139], v[138:139], off offset:288
	v_and_b32_e32 v175, 0xffff0000, v175
	v_pk_add_f32 v[124:125], v[124:125], v[180:181]
	v_pk_add_f32 v[126:127], v[126:127], v[174:175]
	v_mul_f32_e32 v174, v125, v125
	v_fmac_f32_e32 v174, v124, v124
	v_cvt_pk_bf16_f32 v124, v124, v125
	v_cvt_pk_bf16_f32 v125, v126, v127
	v_mul_f32_e32 v175, v127, v127
	global_store_dwordx2 v[156:157], v[124:125], off
	v_lshlrev_b32_e32 v124, 16, v176
	v_and_b32_e32 v125, 0xffff0000, v176
	v_fmac_f32_e32 v175, v126, v126
	v_lshlrev_b32_e32 v126, 16, v177
	v_and_b32_e32 v127, 0xffff0000, v177
	v_pk_add_f32 v[120:121], v[120:121], v[124:125]
	v_pk_add_f32 v[122:123], v[122:123], v[126:127]
	v_mul_f32_e32 v124, v121, v121
	v_fmac_f32_e32 v124, v120, v120
	v_cvt_pk_bf16_f32 v120, v120, v121
	v_cvt_pk_bf16_f32 v121, v122, v123
	v_mul_f32_e32 v125, v123, v123
	global_store_dwordx2 v[156:157], v[120:121], off offset:32
	v_lshlrev_b32_e32 v120, 16, v178
	v_and_b32_e32 v121, 0xffff0000, v178
	v_fmac_f32_e32 v125, v122, v122
	v_lshlrev_b32_e32 v122, 16, v179
	v_and_b32_e32 v123, 0xffff0000, v179
	v_pk_add_f32 v[116:117], v[116:117], v[120:121]
	v_pk_add_f32 v[118:119], v[118:119], v[122:123]
	v_mul_f32_e32 v120, v117, v117
	v_fmac_f32_e32 v120, v116, v116
	v_mul_f32_e32 v121, v119, v119
	v_cvt_pk_bf16_f32 v116, v116, v117
	v_cvt_pk_bf16_f32 v117, v118, v119
	v_fmac_f32_e32 v121, v118, v118
	global_store_dwordx2 v[156:157], v[116:117], off offset:256
	v_lshlrev_b32_e32 v116, 16, v158
	v_and_b32_e32 v117, 0xffff0000, v158
	v_lshlrev_b32_e32 v118, 16, v159
	v_and_b32_e32 v119, 0xffff0000, v159
	v_pk_add_f32 v[114:115], v[114:115], v[118:119]
	v_pk_add_f32 v[112:113], v[112:113], v[116:117]
	v_add_f32_e32 v174, v174, v175
	v_add_f32_e32 v124, v124, v125
	v_mul_f32_e32 v116, v113, v113
	v_mul_f32_e32 v117, v115, v115
	v_add_f32_e32 v124, v174, v124
	v_add_f32_e32 v120, v120, v121
	v_fmac_f32_e32 v116, v112, v112
	v_fmac_f32_e32 v117, v114, v114
	v_add_f32_e32 v120, v124, v120
	v_add_f32_e32 v116, v116, v117
	v_add_f32_e32 v116, v120, v116
	v_cvt_pk_bf16_f32 v112, v112, v113
	v_cvt_pk_bf16_f32 v113, v114, v115
	global_store_dwordx2 v[156:157], v[112:113], off offset:288
	v_mov_b32_e32 v112, v116
	s_nop 1
	v_permlane16_swap_b32_e32 v112, v116
	s_waitcnt lgkmcnt(0)
	v_add_f32_e32 v112, v116, v112
	v_mov_b32_e32 v113, v112
	s_nop 1
	v_permlane32_swap_b32_e32 v113, v112
	s_and_saveexec_b64 s[28:29], s[38:39]
	s_cbranch_execz .LBB0_1212
	s_waitcnt lgkmcnt(0)
	v_add_f32_e32 v112, v112, v113
	ds_write_b32 v162, v112
.LBB0_1212:
	s_or_b64 exec, exec, s[28:29]
	v_mov_b32_e32 v121, v145
	v_add_u32_e32 v120, 0x4000, v144
	s_waitcnt lgkmcnt(0)
	v_lshl_add_u64 v[112:113], v[120:121], 1, s[60:61]
	global_load_dwordx2 v[118:119], v[112:113], off
	global_load_dwordx2 v[116:117], v[112:113], off offset:32
	global_load_dwordx2 v[114:115], v[112:113], off offset:256
	s_nop 0
	global_load_dwordx2 v[112:113], v[112:113], off offset:288
	s_waitcnt vmcnt(11)
	v_lshlrev_b32_e32 v124, 16, v154
	v_and_b32_e32 v125, 0xffff0000, v154
	v_lshlrev_b32_e32 v126, 16, v155
	v_and_b32_e32 v127, 0xffff0000, v155
	v_pk_add_f32 v[108:109], v[108:109], v[124:125]
	v_pk_add_f32 v[110:111], v[110:111], v[126:127]
	v_mul_f32_e32 v121, v109, v109
	v_lshl_add_u64 v[122:123], v[144:145], 1, s[60:61]
	v_fmac_f32_e32 v121, v108, v108
	v_mul_f32_e32 v124, v111, v111
	v_cvt_pk_bf16_f32 v108, v108, v109
	v_cvt_pk_bf16_f32 v109, v110, v111
	v_fmac_f32_e32 v124, v110, v110
	global_store_dwordx2 v[122:123], v[108:109], off
	s_waitcnt vmcnt(11)
	v_lshlrev_b32_e32 v108, 16, v142
	v_and_b32_e32 v109, 0xffff0000, v142
	v_lshlrev_b32_e32 v110, 16, v143
	v_and_b32_e32 v111, 0xffff0000, v143
	v_pk_add_f32 v[106:107], v[106:107], v[110:111]
	v_pk_add_f32 v[104:105], v[104:105], v[108:109]
	v_mul_f32_e32 v109, v107, v107
	v_mul_f32_e32 v108, v105, v105
	v_fmac_f32_e32 v108, v104, v104
	v_fmac_f32_e32 v109, v106, v106
	v_add_f32_e32 v121, v121, v124
	v_add_f32_e32 v108, v108, v109
	v_add_f32_e32 v121, v121, v108
	s_waitcnt vmcnt(10)
	v_lshlrev_b32_e32 v108, 16, v140
	v_and_b32_e32 v109, 0xffff0000, v140
	v_lshlrev_b32_e32 v110, 16, v141
	v_and_b32_e32 v111, 0xffff0000, v141
	v_pk_add_f32 v[102:103], v[102:103], v[110:111]
	v_pk_add_f32 v[100:101], v[100:101], v[108:109]
	v_cvt_pk_bf16_f32 v104, v104, v105
	v_mul_f32_e32 v105, v101, v101
	v_mul_f32_e32 v108, v103, v103
	v_fmac_f32_e32 v105, v100, v100
	v_fmac_f32_e32 v108, v102, v102
	v_add_f32_e32 v105, v105, v108
	s_waitcnt vmcnt(9)
	v_lshlrev_b32_e32 v108, 16, v138
	v_and_b32_e32 v109, 0xffff0000, v138
	v_lshlrev_b32_e32 v110, 16, v139
	v_and_b32_e32 v111, 0xffff0000, v139
	v_pk_add_f32 v[98:99], v[98:99], v[110:111]
	v_pk_add_f32 v[108:109], v[96:97], v[108:109]
	v_mul_f32_e32 v97, v99, v99
	v_mul_f32_e32 v96, v109, v109
	v_fmac_f32_e32 v96, v108, v108
	v_fmac_f32_e32 v97, v98, v98
	v_add_f32_e32 v105, v121, v105
	v_add_f32_e32 v96, v96, v97
	v_add_f32_e32 v96, v105, v96
	v_mov_b32_e32 v97, v96
	s_nop 1
	v_permlane16_swap_b32_e32 v97, v96
	v_cvt_pk_bf16_f32 v100, v100, v101
	v_cvt_pk_bf16_f32 v101, v102, v103
	v_cvt_pk_bf16_f32 v105, v106, v107
	global_store_dwordx2 v[122:123], v[100:101], off offset:256
	s_waitcnt lgkmcnt(0)
	v_add_f32_e32 v96, v96, v97
	v_mov_b32_e32 v97, v96
	s_nop 1
	v_permlane32_swap_b32_e32 v97, v96
	v_cvt_pk_bf16_f32 v100, v108, v109
	v_cvt_pk_bf16_f32 v101, v98, v99
	global_store_dwordx2 v[122:123], v[104:105], off offset:32
	global_store_dwordx2 v[122:123], v[100:101], off offset:288
	s_and_saveexec_b64 s[28:29], s[38:39]
	s_cbranch_execz .LBB0_1214
	s_waitcnt lgkmcnt(0)
	v_add_f32_e32 v96, v96, v97
	ds_write_b32 v163, v96
.LBB0_1214:
	s_or_b64 exec, exec, s[28:29]
	s_waitcnt vmcnt(7)
	v_lshlrev_b32_e32 v106, 16, v118
	v_add_u32_e32 v144, 0x4000, v120
	s_waitcnt lgkmcnt(0)
	v_lshl_add_u64 v[96:97], v[144:145], 1, s[60:61]
	global_load_dwordx2 v[102:103], v[96:97], off
	global_load_dwordx2 v[100:101], v[96:97], off offset:32
	global_load_dwordx2 v[98:99], v[96:97], off offset:256
	s_nop 0
	global_load_dwordx2 v[96:97], v[96:97], off offset:288
	v_and_b32_e32 v107, 0xffff0000, v118
	v_lshlrev_b32_e32 v108, 16, v119
	v_and_b32_e32 v109, 0xffff0000, v119
	v_pk_add_f32 v[92:93], v[92:93], v[106:107]
	v_mov_b32_e32 v121, v145
	v_pk_add_f32 v[94:95], v[94:95], v[108:109]
	v_mul_f32_e32 v106, v93, v93
	v_lshl_add_u64 v[104:105], v[120:121], 1, s[60:61]
	v_fmac_f32_e32 v106, v92, v92
	v_mul_f32_e32 v107, v95, v95
	v_cvt_pk_bf16_f32 v92, v92, v93
	v_cvt_pk_bf16_f32 v93, v94, v95
	v_fmac_f32_e32 v107, v94, v94
	global_store_dwordx2 v[104:105], v[92:93], off
	s_waitcnt vmcnt(11)
	v_lshlrev_b32_e32 v92, 16, v116
	v_and_b32_e32 v93, 0xffff0000, v116
	v_lshlrev_b32_e32 v94, 16, v117
	v_and_b32_e32 v95, 0xffff0000, v117
	v_pk_add_f32 v[90:91], v[90:91], v[94:95]
	v_pk_add_f32 v[88:89], v[88:89], v[92:93]
	v_mul_f32_e32 v93, v91, v91
	v_mul_f32_e32 v92, v89, v89
	v_fmac_f32_e32 v92, v88, v88
	v_fmac_f32_e32 v93, v90, v90
	v_add_f32_e32 v106, v106, v107
	v_add_f32_e32 v92, v92, v93
	v_add_f32_e32 v106, v106, v92
	s_waitcnt vmcnt(10)
	v_lshlrev_b32_e32 v92, 16, v114
	v_and_b32_e32 v93, 0xffff0000, v114
	v_lshlrev_b32_e32 v94, 16, v115
	v_and_b32_e32 v95, 0xffff0000, v115
	v_pk_add_f32 v[86:87], v[86:87], v[94:95]
	v_pk_add_f32 v[84:85], v[84:85], v[92:93]
	v_cvt_pk_bf16_f32 v88, v88, v89
	v_mul_f32_e32 v89, v85, v85
	v_mul_f32_e32 v92, v87, v87
	v_fmac_f32_e32 v89, v84, v84
	v_fmac_f32_e32 v92, v86, v86
	v_add_f32_e32 v89, v89, v92
	s_waitcnt vmcnt(9)
	v_lshlrev_b32_e32 v92, 16, v112
	v_and_b32_e32 v93, 0xffff0000, v112
	v_lshlrev_b32_e32 v94, 16, v113
	v_and_b32_e32 v95, 0xffff0000, v113
	v_pk_add_f32 v[82:83], v[82:83], v[94:95]
	v_pk_add_f32 v[92:93], v[80:81], v[92:93]
	v_mul_f32_e32 v81, v83, v83
	v_mul_f32_e32 v80, v93, v93
	v_fmac_f32_e32 v80, v92, v92
	v_fmac_f32_e32 v81, v82, v82
	v_add_f32_e32 v89, v106, v89
	v_add_f32_e32 v80, v80, v81
	v_add_f32_e32 v80, v89, v80
	v_mov_b32_e32 v81, v80
	s_nop 1
	v_permlane16_swap_b32_e32 v81, v80
	v_cvt_pk_bf16_f32 v84, v84, v85
	v_cvt_pk_bf16_f32 v85, v86, v87
	v_cvt_pk_bf16_f32 v89, v90, v91
	global_store_dwordx2 v[104:105], v[84:85], off offset:256
	s_waitcnt lgkmcnt(0)
	v_add_f32_e32 v80, v80, v81
	v_mov_b32_e32 v81, v80
	s_nop 1
	v_permlane32_swap_b32_e32 v81, v80
	v_cvt_pk_bf16_f32 v84, v92, v93
	v_cvt_pk_bf16_f32 v85, v82, v83
	global_store_dwordx2 v[104:105], v[88:89], off offset:32
	global_store_dwordx2 v[104:105], v[84:85], off offset:288
	s_and_saveexec_b64 s[28:29], s[38:39]
	s_cbranch_execz .LBB0_1216
	s_waitcnt lgkmcnt(0)
	v_add_f32_e32 v80, v80, v81
	ds_write_b32 v164, v80
.LBB0_1216:
	s_or_b64 exec, exec, s[28:29]
	v_mov_b32_e32 v89, v145
	v_add_u32_e32 v88, 0x14000, v144
	s_waitcnt lgkmcnt(0)
	v_lshl_add_u64 v[80:81], v[88:89], 1, s[60:61]
	global_load_dwordx2 v[86:87], v[80:81], off
	global_load_dwordx2 v[84:85], v[80:81], off offset:32
	global_load_dwordx2 v[82:83], v[80:81], off offset:256
	s_nop 0
	global_load_dwordx2 v[80:81], v[80:81], off offset:288
	s_waitcnt vmcnt(11)
	v_lshlrev_b32_e32 v92, 16, v102
	v_and_b32_e32 v93, 0xffff0000, v102
	v_lshlrev_b32_e32 v94, 16, v103
	v_and_b32_e32 v95, 0xffff0000, v103
	v_pk_add_f32 v[76:77], v[76:77], v[92:93]
	v_pk_add_f32 v[78:79], v[78:79], v[94:95]
	v_mul_f32_e32 v89, v77, v77
	v_lshl_add_u64 v[90:91], v[144:145], 1, s[60:61]
	v_fmac_f32_e32 v89, v76, v76
	v_mul_f32_e32 v92, v79, v79
	v_cvt_pk_bf16_f32 v76, v76, v77
	v_cvt_pk_bf16_f32 v77, v78, v79
	v_fmac_f32_e32 v92, v78, v78
	global_store_dwordx2 v[90:91], v[76:77], off
	s_waitcnt vmcnt(11)
	v_lshlrev_b32_e32 v76, 16, v100
	v_and_b32_e32 v77, 0xffff0000, v100
	v_lshlrev_b32_e32 v78, 16, v101
	v_and_b32_e32 v79, 0xffff0000, v101
	v_pk_add_f32 v[74:75], v[74:75], v[78:79]
	v_pk_add_f32 v[72:73], v[72:73], v[76:77]
	v_mul_f32_e32 v77, v75, v75
	v_mul_f32_e32 v76, v73, v73
	v_fmac_f32_e32 v76, v72, v72
	v_fmac_f32_e32 v77, v74, v74
	v_add_f32_e32 v89, v89, v92
	v_add_f32_e32 v76, v76, v77
	v_add_f32_e32 v89, v89, v76
	s_waitcnt vmcnt(10)
	v_lshlrev_b32_e32 v76, 16, v98
	v_and_b32_e32 v77, 0xffff0000, v98
	v_lshlrev_b32_e32 v78, 16, v99
	v_and_b32_e32 v79, 0xffff0000, v99
	v_pk_add_f32 v[70:71], v[70:71], v[78:79]
	v_pk_add_f32 v[68:69], v[68:69], v[76:77]
	v_cvt_pk_bf16_f32 v72, v72, v73
	v_mul_f32_e32 v73, v69, v69
	v_mul_f32_e32 v76, v71, v71
	v_fmac_f32_e32 v73, v68, v68
	v_fmac_f32_e32 v76, v70, v70
	v_add_f32_e32 v73, v73, v76
	s_waitcnt vmcnt(9)
	v_lshlrev_b32_e32 v76, 16, v96
	v_and_b32_e32 v77, 0xffff0000, v96
	v_lshlrev_b32_e32 v78, 16, v97
	v_and_b32_e32 v79, 0xffff0000, v97
	v_pk_add_f32 v[66:67], v[66:67], v[78:79]
	v_pk_add_f32 v[76:77], v[64:65], v[76:77]
	v_mul_f32_e32 v65, v67, v67
	v_mul_f32_e32 v64, v77, v77
	v_fmac_f32_e32 v64, v76, v76
	v_fmac_f32_e32 v65, v66, v66
	v_add_f32_e32 v73, v89, v73
	v_add_f32_e32 v64, v64, v65
	v_add_f32_e32 v64, v73, v64
	v_mov_b32_e32 v65, v64
	s_nop 1
	v_permlane16_swap_b32_e32 v65, v64
	v_cvt_pk_bf16_f32 v68, v68, v69
	v_cvt_pk_bf16_f32 v69, v70, v71
	v_cvt_pk_bf16_f32 v73, v74, v75
	global_store_dwordx2 v[90:91], v[68:69], off offset:256
	s_waitcnt lgkmcnt(0)
	v_add_f32_e32 v64, v64, v65
	v_mov_b32_e32 v65, v64
	s_nop 1
	v_permlane32_swap_b32_e32 v65, v64
	v_cvt_pk_bf16_f32 v68, v76, v77
	v_cvt_pk_bf16_f32 v69, v66, v67
	global_store_dwordx2 v[90:91], v[72:73], off offset:32
	global_store_dwordx2 v[90:91], v[68:69], off offset:288
	s_and_saveexec_b64 s[28:29], s[38:39]
	s_cbranch_execz .LBB0_1218
	s_waitcnt lgkmcnt(0)
	v_add_f32_e32 v64, v64, v65
	ds_write_b32 v165, v64
.LBB0_1218:
	s_or_b64 exec, exec, s[28:29]
	s_waitcnt vmcnt(7)
	v_lshlrev_b32_e32 v74, 16, v86
	v_add_u32_e32 v144, 0x4000, v88
	s_waitcnt lgkmcnt(0)
	v_lshl_add_u64 v[64:65], v[144:145], 1, s[60:61]
	global_load_dwordx2 v[70:71], v[64:65], off
	global_load_dwordx2 v[68:69], v[64:65], off offset:32
	global_load_dwordx2 v[66:67], v[64:65], off offset:256
	s_nop 0
	global_load_dwordx2 v[64:65], v[64:65], off offset:288
	v_and_b32_e32 v75, 0xffff0000, v86
	v_lshlrev_b32_e32 v76, 16, v87
	v_and_b32_e32 v77, 0xffff0000, v87
	v_pk_add_f32 v[60:61], v[60:61], v[74:75]
	v_mov_b32_e32 v89, v145
	v_pk_add_f32 v[62:63], v[62:63], v[76:77]
	v_mul_f32_e32 v74, v61, v61
	v_lshl_add_u64 v[72:73], v[88:89], 1, s[60:61]
	v_fmac_f32_e32 v74, v60, v60
	v_mul_f32_e32 v75, v63, v63
	v_cvt_pk_bf16_f32 v60, v60, v61
	v_cvt_pk_bf16_f32 v61, v62, v63
	v_fmac_f32_e32 v75, v62, v62
	global_store_dwordx2 v[72:73], v[60:61], off
	s_waitcnt vmcnt(11)
	v_lshlrev_b32_e32 v60, 16, v84
	v_and_b32_e32 v61, 0xffff0000, v84
	v_lshlrev_b32_e32 v62, 16, v85
	v_and_b32_e32 v63, 0xffff0000, v85
	v_pk_add_f32 v[58:59], v[58:59], v[62:63]
	v_pk_add_f32 v[56:57], v[56:57], v[60:61]
	v_mul_f32_e32 v61, v59, v59
	v_mul_f32_e32 v60, v57, v57
	v_fmac_f32_e32 v60, v56, v56
	v_fmac_f32_e32 v61, v58, v58
	v_add_f32_e32 v74, v74, v75
	v_add_f32_e32 v60, v60, v61
	v_add_f32_e32 v74, v74, v60
	s_waitcnt vmcnt(10)
	v_lshlrev_b32_e32 v60, 16, v82
	v_and_b32_e32 v61, 0xffff0000, v82
	v_lshlrev_b32_e32 v62, 16, v83
	v_and_b32_e32 v63, 0xffff0000, v83
	v_pk_add_f32 v[54:55], v[54:55], v[62:63]
	v_pk_add_f32 v[52:53], v[52:53], v[60:61]
	v_cvt_pk_bf16_f32 v56, v56, v57
	v_mul_f32_e32 v57, v53, v53
	v_mul_f32_e32 v60, v55, v55
	v_fmac_f32_e32 v57, v52, v52
	v_fmac_f32_e32 v60, v54, v54
	v_add_f32_e32 v57, v57, v60
	s_waitcnt vmcnt(9)
	v_lshlrev_b32_e32 v60, 16, v80
	v_and_b32_e32 v61, 0xffff0000, v80
	v_lshlrev_b32_e32 v62, 16, v81
	v_and_b32_e32 v63, 0xffff0000, v81
	v_pk_add_f32 v[50:51], v[50:51], v[62:63]
	v_pk_add_f32 v[60:61], v[48:49], v[60:61]
	v_mul_f32_e32 v49, v51, v51
	v_mul_f32_e32 v48, v61, v61
	v_fmac_f32_e32 v48, v60, v60
	v_fmac_f32_e32 v49, v50, v50
	v_add_f32_e32 v57, v74, v57
	v_add_f32_e32 v48, v48, v49
	v_add_f32_e32 v48, v57, v48
	v_mov_b32_e32 v49, v48
	s_nop 1
	v_permlane16_swap_b32_e32 v49, v48
	v_cvt_pk_bf16_f32 v52, v52, v53
	v_cvt_pk_bf16_f32 v53, v54, v55
	v_cvt_pk_bf16_f32 v57, v58, v59
	global_store_dwordx2 v[72:73], v[52:53], off offset:256
	s_waitcnt lgkmcnt(0)
	v_add_f32_e32 v48, v48, v49
	v_mov_b32_e32 v49, v48
	s_nop 1
	v_permlane32_swap_b32_e32 v49, v48
	v_cvt_pk_bf16_f32 v52, v60, v61
	v_cvt_pk_bf16_f32 v53, v50, v51
	global_store_dwordx2 v[72:73], v[56:57], off offset:32
	global_store_dwordx2 v[72:73], v[52:53], off offset:288
	s_and_saveexec_b64 s[28:29], s[38:39]
	s_cbranch_execz .LBB0_1220
	s_waitcnt lgkmcnt(0)
	v_add_f32_e32 v48, v48, v49
	ds_write_b32 v166, v48
.LBB0_1220:
	s_or_b64 exec, exec, s[28:29]
	v_mov_b32_e32 v57, v145
	v_add_u32_e32 v56, 0x4000, v144
	s_waitcnt lgkmcnt(0)
	v_lshl_add_u64 v[48:49], v[56:57], 1, s[60:61]
	global_load_dwordx2 v[54:55], v[48:49], off
	global_load_dwordx2 v[52:53], v[48:49], off offset:32
	global_load_dwordx2 v[50:51], v[48:49], off offset:256
	s_nop 0
	global_load_dwordx2 v[48:49], v[48:49], off offset:288
	s_waitcnt vmcnt(11)
	v_lshlrev_b32_e32 v60, 16, v70
	v_and_b32_e32 v61, 0xffff0000, v70
	v_lshlrev_b32_e32 v62, 16, v71
	v_and_b32_e32 v63, 0xffff0000, v71
	v_pk_add_f32 v[44:45], v[44:45], v[60:61]
	v_pk_add_f32 v[46:47], v[46:47], v[62:63]
	v_mul_f32_e32 v57, v45, v45
	v_lshl_add_u64 v[58:59], v[144:145], 1, s[60:61]
	v_fmac_f32_e32 v57, v44, v44
	v_mul_f32_e32 v60, v47, v47
	v_cvt_pk_bf16_f32 v44, v44, v45
	v_cvt_pk_bf16_f32 v45, v46, v47
	v_fmac_f32_e32 v60, v46, v46
	global_store_dwordx2 v[58:59], v[44:45], off
	s_waitcnt vmcnt(11)
	v_lshlrev_b32_e32 v44, 16, v68
	v_and_b32_e32 v45, 0xffff0000, v68
	v_lshlrev_b32_e32 v46, 16, v69
	v_and_b32_e32 v47, 0xffff0000, v69
	v_pk_add_f32 v[42:43], v[42:43], v[46:47]
	v_pk_add_f32 v[40:41], v[40:41], v[44:45]
	v_mul_f32_e32 v45, v43, v43
	v_mul_f32_e32 v44, v41, v41
	v_fmac_f32_e32 v44, v40, v40
	v_fmac_f32_e32 v45, v42, v42
	v_add_f32_e32 v57, v57, v60
	v_add_f32_e32 v44, v44, v45
	v_add_f32_e32 v57, v57, v44
	s_waitcnt vmcnt(10)
	v_lshlrev_b32_e32 v44, 16, v66
	v_and_b32_e32 v45, 0xffff0000, v66
	v_lshlrev_b32_e32 v46, 16, v67
	v_and_b32_e32 v47, 0xffff0000, v67
	v_pk_add_f32 v[38:39], v[38:39], v[46:47]
	v_pk_add_f32 v[36:37], v[36:37], v[44:45]
	v_cvt_pk_bf16_f32 v40, v40, v41
	v_mul_f32_e32 v41, v37, v37
	v_mul_f32_e32 v44, v39, v39
	v_fmac_f32_e32 v41, v36, v36
	v_fmac_f32_e32 v44, v38, v38
	v_add_f32_e32 v41, v41, v44
	s_waitcnt vmcnt(9)
	v_lshlrev_b32_e32 v44, 16, v64
	v_and_b32_e32 v45, 0xffff0000, v64
	v_lshlrev_b32_e32 v46, 16, v65
	v_and_b32_e32 v47, 0xffff0000, v65
	v_pk_add_f32 v[34:35], v[34:35], v[46:47]
	v_pk_add_f32 v[44:45], v[32:33], v[44:45]
	v_mul_f32_e32 v33, v35, v35
	v_mul_f32_e32 v32, v45, v45
	v_fmac_f32_e32 v32, v44, v44
	v_fmac_f32_e32 v33, v34, v34
	v_add_f32_e32 v41, v57, v41
	v_add_f32_e32 v32, v32, v33
	v_add_f32_e32 v32, v41, v32
	v_mov_b32_e32 v33, v32
	s_nop 1
	v_permlane16_swap_b32_e32 v33, v32
	v_cvt_pk_bf16_f32 v36, v36, v37
	v_cvt_pk_bf16_f32 v37, v38, v39
	v_cvt_pk_bf16_f32 v41, v42, v43
	global_store_dwordx2 v[58:59], v[36:37], off offset:256
	s_waitcnt lgkmcnt(0)
	v_add_f32_e32 v32, v32, v33
	v_mov_b32_e32 v33, v32
	s_nop 1
	v_permlane32_swap_b32_e32 v33, v32
	v_cvt_pk_bf16_f32 v36, v44, v45
	v_cvt_pk_bf16_f32 v37, v34, v35
	global_store_dwordx2 v[58:59], v[40:41], off offset:32
	global_store_dwordx2 v[58:59], v[36:37], off offset:288
	s_and_saveexec_b64 s[28:29], s[38:39]
	s_cbranch_execz .LBB0_1222
	s_waitcnt lgkmcnt(0)
	v_add_f32_e32 v32, v32, v33
	ds_write_b32 v167, v32
.LBB0_1222:
	s_or_b64 exec, exec, s[28:29]
	s_waitcnt vmcnt(7)
	v_lshlrev_b32_e32 v42, 16, v54
	v_add_u32_e32 v144, 0x4000, v56
	s_waitcnt lgkmcnt(0)
	v_lshl_add_u64 v[32:33], v[144:145], 1, s[60:61]
	global_load_dwordx2 v[38:39], v[32:33], off
	global_load_dwordx2 v[36:37], v[32:33], off offset:32
	global_load_dwordx2 v[34:35], v[32:33], off offset:256
	s_nop 0
	global_load_dwordx2 v[32:33], v[32:33], off offset:288
	v_and_b32_e32 v43, 0xffff0000, v54
	v_lshlrev_b32_e32 v44, 16, v55
	v_and_b32_e32 v45, 0xffff0000, v55
	v_pk_add_f32 v[28:29], v[28:29], v[42:43]
	v_mov_b32_e32 v57, v145
	v_pk_add_f32 v[30:31], v[30:31], v[44:45]
	v_mul_f32_e32 v42, v29, v29
	v_lshl_add_u64 v[40:41], v[56:57], 1, s[60:61]
	v_fmac_f32_e32 v42, v28, v28
	v_mul_f32_e32 v43, v31, v31
	v_cvt_pk_bf16_f32 v28, v28, v29
	v_cvt_pk_bf16_f32 v29, v30, v31
	v_fmac_f32_e32 v43, v30, v30
	global_store_dwordx2 v[40:41], v[28:29], off
	s_waitcnt vmcnt(11)
	v_lshlrev_b32_e32 v28, 16, v52
	v_and_b32_e32 v29, 0xffff0000, v52
	v_lshlrev_b32_e32 v30, 16, v53
	v_and_b32_e32 v31, 0xffff0000, v53
	v_pk_add_f32 v[26:27], v[26:27], v[30:31]
	v_pk_add_f32 v[24:25], v[24:25], v[28:29]
	v_mul_f32_e32 v29, v27, v27
	v_mul_f32_e32 v28, v25, v25
	v_fmac_f32_e32 v28, v24, v24
	v_fmac_f32_e32 v29, v26, v26
	v_add_f32_e32 v42, v42, v43
	v_add_f32_e32 v28, v28, v29
	v_add_f32_e32 v42, v42, v28
	s_waitcnt vmcnt(10)
	v_lshlrev_b32_e32 v28, 16, v50
	v_and_b32_e32 v29, 0xffff0000, v50
	v_lshlrev_b32_e32 v30, 16, v51
	v_and_b32_e32 v31, 0xffff0000, v51
	v_pk_add_f32 v[22:23], v[22:23], v[30:31]
	v_pk_add_f32 v[20:21], v[20:21], v[28:29]
	v_cvt_pk_bf16_f32 v24, v24, v25
	v_mul_f32_e32 v25, v21, v21
	v_mul_f32_e32 v28, v23, v23
	v_fmac_f32_e32 v25, v20, v20
	v_fmac_f32_e32 v28, v22, v22
	v_add_f32_e32 v25, v25, v28
	s_waitcnt vmcnt(9)
	v_lshlrev_b32_e32 v28, 16, v48
	v_and_b32_e32 v29, 0xffff0000, v48
	v_lshlrev_b32_e32 v30, 16, v49
	v_and_b32_e32 v31, 0xffff0000, v49
	v_pk_add_f32 v[18:19], v[18:19], v[30:31]
	v_pk_add_f32 v[28:29], v[16:17], v[28:29]
	v_mul_f32_e32 v17, v19, v19
	v_mul_f32_e32 v16, v29, v29
	v_fmac_f32_e32 v16, v28, v28
	v_fmac_f32_e32 v17, v18, v18
	v_add_f32_e32 v25, v42, v25
	v_add_f32_e32 v16, v16, v17
	v_add_f32_e32 v16, v25, v16
	v_mov_b32_e32 v17, v16
	s_nop 1
	v_permlane16_swap_b32_e32 v17, v16
	v_cvt_pk_bf16_f32 v20, v20, v21
	v_cvt_pk_bf16_f32 v21, v22, v23
	v_cvt_pk_bf16_f32 v25, v26, v27
	global_store_dwordx2 v[40:41], v[20:21], off offset:256
	s_waitcnt lgkmcnt(0)
	v_add_f32_e32 v16, v16, v17
	v_mov_b32_e32 v17, v16
	s_nop 1
	v_permlane32_swap_b32_e32 v17, v16
	v_cvt_pk_bf16_f32 v20, v28, v29
	v_cvt_pk_bf16_f32 v21, v18, v19
	global_store_dwordx2 v[40:41], v[24:25], off offset:32
	global_store_dwordx2 v[40:41], v[20:21], off offset:288
	s_and_saveexec_b64 s[28:29], s[38:39]
	s_cbranch_execz .LBB0_1224
	s_waitcnt lgkmcnt(0)
	v_add_f32_e32 v16, v16, v17
	ds_write_b32 v168, v16
.LBB0_1224:
	s_or_b64 exec, exec, s[28:29]
	s_waitcnt vmcnt(7)
	v_lshlrev_b32_e32 v16, 16, v38
	s_waitcnt lgkmcnt(0)
	v_and_b32_e32 v17, 0xffff0000, v38
	v_lshlrev_b32_e32 v18, 16, v39
	v_and_b32_e32 v19, 0xffff0000, v39
	v_pk_add_f32 v[12:13], v[12:13], v[16:17]
	v_pk_add_f32 v[14:15], v[14:15], v[18:19]
	v_mul_f32_e32 v16, v13, v13
	v_fmac_f32_e32 v16, v12, v12
	v_lshl_add_u64 v[20:21], v[144:145], 1, s[60:61]
	v_mul_f32_e32 v17, v15, v15
	v_cvt_pk_bf16_f32 v12, v12, v13
	v_cvt_pk_bf16_f32 v13, v14, v15
	v_fmac_f32_e32 v17, v14, v14
	global_store_dwordx2 v[20:21], v[12:13], off
	s_waitcnt vmcnt(7)
	v_lshlrev_b32_e32 v12, 16, v36
	v_and_b32_e32 v13, 0xffff0000, v36
	v_lshlrev_b32_e32 v14, 16, v37
	v_and_b32_e32 v15, 0xffff0000, v37
	v_pk_add_f32 v[10:11], v[10:11], v[14:15]
	v_pk_add_f32 v[8:9], v[8:9], v[12:13]
	v_mul_f32_e32 v13, v11, v11
	v_mul_f32_e32 v12, v9, v9
	v_fmac_f32_e32 v12, v8, v8
	v_fmac_f32_e32 v13, v10, v10
	v_add_f32_e32 v16, v16, v17
	v_add_f32_e32 v12, v12, v13
	v_add_f32_e32 v16, v16, v12
	s_waitcnt vmcnt(6)
	v_lshlrev_b32_e32 v12, 16, v34
	v_and_b32_e32 v13, 0xffff0000, v34
	v_lshlrev_b32_e32 v14, 16, v35
	v_and_b32_e32 v15, 0xffff0000, v35
	v_pk_add_f32 v[6:7], v[6:7], v[14:15]
	v_pk_add_f32 v[4:5], v[4:5], v[12:13]
	v_cvt_pk_bf16_f32 v8, v8, v9
	v_mul_f32_e32 v9, v5, v5
	v_mul_f32_e32 v12, v7, v7
	v_fmac_f32_e32 v9, v4, v4
	v_fmac_f32_e32 v12, v6, v6
	v_add_f32_e32 v9, v9, v12
	s_waitcnt vmcnt(5)
	v_lshlrev_b32_e32 v12, 16, v32
	v_and_b32_e32 v13, 0xffff0000, v32
	v_lshlrev_b32_e32 v14, 16, v33
	v_and_b32_e32 v15, 0xffff0000, v33
	v_pk_add_f32 v[2:3], v[2:3], v[14:15]
	v_pk_add_f32 v[12:13], v[0:1], v[12:13]
	v_mul_f32_e32 v1, v3, v3
	v_mul_f32_e32 v0, v13, v13
	v_fmac_f32_e32 v0, v12, v12
	v_fmac_f32_e32 v1, v2, v2
	v_add_f32_e32 v9, v16, v9
	v_add_f32_e32 v0, v0, v1
	v_add_f32_e32 v0, v9, v0
	v_mov_b32_e32 v1, v0
	s_nop 1
	v_permlane16_swap_b32_e32 v1, v0
	v_cvt_pk_bf16_f32 v4, v4, v5
	v_cvt_pk_bf16_f32 v5, v6, v7
	v_cvt_pk_bf16_f32 v9, v10, v11
	global_store_dwordx2 v[20:21], v[4:5], off offset:256
	s_waitcnt lgkmcnt(0)
	v_add_f32_e32 v0, v0, v1
	v_mov_b32_e32 v1, v0
	s_nop 1
	v_permlane32_swap_b32_e32 v1, v0
	v_cvt_pk_bf16_f32 v4, v12, v13
	v_cvt_pk_bf16_f32 v5, v2, v3
	global_store_dwordx2 v[20:21], v[8:9], off offset:32
	global_store_dwordx2 v[20:21], v[4:5], off offset:288
	s_and_saveexec_b64 s[28:29], s[38:39]
	s_cbranch_execz .LBB0_1226
	s_waitcnt lgkmcnt(0)
	v_add_f32_e32 v0, v0, v1
	ds_write_b32 v169, v0

.LBB0_1402:
	s_ashr_i32 s47, s46, 31
	s_lshl_b64 s[4:5], s[46:47], 19
	s_add_u32 s54, s0, s4
	s_addc_u32 s55, s1, s5
	v_lshl_add_u32 v144, s2, 8, v161
	v_lshl_add_u64 v[156:157], v[144:145], 1, s[54:55]
	global_load_dwordx2 v[174:175], v[156:157], off
	global_load_dwordx2 v[176:177], v[156:157], off offset:32
	global_load_dwordx2 v[178:179], v[156:157], off offset:256
	global_load_dwordx2 v[158:159], v[156:157], off offset:288
	v_and_b32_e32 v139, 64, v183
	v_xor_b32_e32 v138, 16, v183
	v_add_u32_e32 v139, 64, v139
	v_cmp_lt_i32_e32 vcc, v138, v139
	v_add_u32_e32 v144, 0x4000, v144
	s_waitcnt vmcnt(0)
	v_lshlrev_b32_e32 v180, 16, v174
	v_cndmask_b32_e32 v138, v183, v138, vcc
	v_lshlrev_b32_e32 v173, 2, v138
	v_xor_b32_e32 v138, 32, v183
	v_cmp_lt_i32_e32 vcc, v138, v139
	v_and_b32_e32 v181, 0xffff0000, v174
	v_lshlrev_b32_e32 v174, 16, v175
	v_cndmask_b32_e32 v138, v183, v138, vcc
	v_lshlrev_b32_e32 v172, 2, v138
	v_lshl_add_u64 v[138:139], v[144:145], 1, s[54:55]
	global_load_dwordx2 v[154:155], v[138:139], off
	global_load_dwordx2 v[142:143], v[138:139], off offset:32
	global_load_dwordx2 v[140:141], v[138:139], off offset:256
	s_nop 0
	global_load_dwordx2 v[138:139], v[138:139], off offset:288
	v_and_b32_e32 v175, 0xffff0000, v175
	v_pk_fma_f32 v[124:125], v[124:125], 0.5, v[180:181] op_sel_hi:[1,0,1]
	v_pk_fma_f32 v[126:127], v[126:127], 0.5, v[174:175] op_sel_hi:[1,0,1]
	v_mul_f32_e32 v174, v125, v125
	v_fmac_f32_e32 v174, v124, v124
	v_cvt_pk_bf16_f32 v124, v124, v125
	v_cvt_pk_bf16_f32 v125, v126, v127
	v_mul_f32_e32 v175, v127, v127
	global_store_dwordx2 v[156:157], v[124:125], off
	v_lshlrev_b32_e32 v124, 16, v176
	v_and_b32_e32 v125, 0xffff0000, v176
	v_fmac_f32_e32 v175, v126, v126
	v_lshlrev_b32_e32 v126, 16, v177
	v_and_b32_e32 v127, 0xffff0000, v177
	v_pk_fma_f32 v[120:121], v[120:121], 0.5, v[124:125] op_sel_hi:[1,0,1]
	v_pk_fma_f32 v[122:123], v[122:123], 0.5, v[126:127] op_sel_hi:[1,0,1]
	v_mul_f32_e32 v124, v121, v121
	v_fmac_f32_e32 v124, v120, v120
	v_cvt_pk_bf16_f32 v120, v120, v121
	v_cvt_pk_bf16_f32 v121, v122, v123
	v_mul_f32_e32 v125, v123, v123
	global_store_dwordx2 v[156:157], v[120:121], off offset:32
	v_lshlrev_b32_e32 v120, 16, v178
	v_and_b32_e32 v121, 0xffff0000, v178
	v_fmac_f32_e32 v125, v122, v122
	v_lshlrev_b32_e32 v122, 16, v179
	v_and_b32_e32 v123, 0xffff0000, v179
	v_pk_fma_f32 v[116:117], v[116:117], 0.5, v[120:121] op_sel_hi:[1,0,1]
	v_pk_fma_f32 v[118:119], v[118:119], 0.5, v[122:123] op_sel_hi:[1,0,1]
	v_mul_f32_e32 v120, v117, v117
	v_fmac_f32_e32 v120, v116, v116
	v_mul_f32_e32 v121, v119, v119
	v_cvt_pk_bf16_f32 v116, v116, v117
	v_cvt_pk_bf16_f32 v117, v118, v119
	v_fmac_f32_e32 v121, v118, v118
	global_store_dwordx2 v[156:157], v[116:117], off offset:256
	v_lshlrev_b32_e32 v116, 16, v158
	v_and_b32_e32 v117, 0xffff0000, v158
	v_lshlrev_b32_e32 v118, 16, v159
	v_and_b32_e32 v119, 0xffff0000, v159
	v_pk_fma_f32 v[114:115], v[114:115], 0.5, v[118:119] op_sel_hi:[1,0,1]
	v_pk_fma_f32 v[112:113], v[112:113], 0.5, v[116:117] op_sel_hi:[1,0,1]
	v_add_f32_e32 v174, v174, v175
	v_add_f32_e32 v124, v124, v125
	v_mul_f32_e32 v116, v113, v113
	v_mul_f32_e32 v117, v115, v115
	v_add_f32_e32 v124, v174, v124
	v_add_f32_e32 v120, v120, v121
	v_fmac_f32_e32 v116, v112, v112
	v_fmac_f32_e32 v117, v114, v114
	v_add_f32_e32 v120, v124, v120
	v_add_f32_e32 v116, v116, v117
	v_add_f32_e32 v116, v120, v116
	v_cvt_pk_bf16_f32 v112, v112, v113
	v_cvt_pk_bf16_f32 v113, v114, v115
	global_store_dwordx2 v[156:157], v[112:113], off offset:288
	v_mov_b32_e32 v112, v116
	s_nop 1
	v_permlane16_swap_b32_e32 v112, v116
	s_waitcnt lgkmcnt(0)
	v_add_f32_e32 v112, v116, v112
	v_mov_b32_e32 v113, v112
	s_nop 1
	v_permlane32_swap_b32_e32 v113, v112
	s_and_saveexec_b64 s[28:29], s[38:39]
	s_cbranch_execz .LBB0_1404
	s_waitcnt lgkmcnt(0)
	v_add_f32_e32 v112, v112, v113
	ds_write_b32 v162, v112
.LBB0_1404:
	s_or_b64 exec, exec, s[28:29]
	v_mov_b32_e32 v121, v145
	v_add_u32_e32 v120, 0x4000, v144
	s_waitcnt lgkmcnt(0)
	v_lshl_add_u64 v[112:113], v[120:121], 1, s[54:55]
	global_load_dwordx2 v[118:119], v[112:113], off
	global_load_dwordx2 v[116:117], v[112:113], off offset:32
	global_load_dwordx2 v[114:115], v[112:113], off offset:256
	s_nop 0
	global_load_dwordx2 v[112:113], v[112:113], off offset:288
	s_waitcnt vmcnt(11)
	v_lshlrev_b32_e32 v124, 16, v154
	v_and_b32_e32 v125, 0xffff0000, v154
	v_lshlrev_b32_e32 v126, 16, v155
	v_and_b32_e32 v127, 0xffff0000, v155
	v_pk_fma_f32 v[108:109], v[108:109], 0.5, v[124:125] op_sel_hi:[1,0,1]
	v_pk_fma_f32 v[110:111], v[110:111], 0.5, v[126:127] op_sel_hi:[1,0,1]
	v_mul_f32_e32 v121, v109, v109
	v_lshl_add_u64 v[122:123], v[144:145], 1, s[54:55]
	v_fmac_f32_e32 v121, v108, v108
	v_mul_f32_e32 v124, v111, v111
	v_cvt_pk_bf16_f32 v108, v108, v109
	v_cvt_pk_bf16_f32 v109, v110, v111
	v_fmac_f32_e32 v124, v110, v110
	global_store_dwordx2 v[122:123], v[108:109], off
	s_waitcnt vmcnt(11)
	v_lshlrev_b32_e32 v108, 16, v142
	v_and_b32_e32 v109, 0xffff0000, v142
	v_lshlrev_b32_e32 v110, 16, v143
	v_and_b32_e32 v111, 0xffff0000, v143
	v_pk_fma_f32 v[106:107], v[106:107], 0.5, v[110:111] op_sel_hi:[1,0,1]
	v_pk_fma_f32 v[104:105], v[104:105], 0.5, v[108:109] op_sel_hi:[1,0,1]
	v_mul_f32_e32 v109, v107, v107
	v_mul_f32_e32 v108, v105, v105
	v_fmac_f32_e32 v108, v104, v104
	v_fmac_f32_e32 v109, v106, v106
	v_add_f32_e32 v121, v121, v124
	v_add_f32_e32 v108, v108, v109
	v_add_f32_e32 v121, v121, v108
	s_waitcnt vmcnt(10)
	v_lshlrev_b32_e32 v108, 16, v140
	v_and_b32_e32 v109, 0xffff0000, v140
	v_lshlrev_b32_e32 v110, 16, v141
	v_and_b32_e32 v111, 0xffff0000, v141
	v_pk_fma_f32 v[102:103], v[102:103], 0.5, v[110:111] op_sel_hi:[1,0,1]
	v_pk_fma_f32 v[100:101], v[100:101], 0.5, v[108:109] op_sel_hi:[1,0,1]
	v_cvt_pk_bf16_f32 v104, v104, v105
	v_mul_f32_e32 v105, v101, v101
	v_mul_f32_e32 v108, v103, v103
	v_fmac_f32_e32 v105, v100, v100
	v_fmac_f32_e32 v108, v102, v102
	v_add_f32_e32 v105, v105, v108
	s_waitcnt vmcnt(9)
	v_lshlrev_b32_e32 v108, 16, v138
	v_and_b32_e32 v109, 0xffff0000, v138
	v_lshlrev_b32_e32 v110, 16, v139
	v_and_b32_e32 v111, 0xffff0000, v139
	v_pk_fma_f32 v[98:99], v[98:99], 0.5, v[110:111] op_sel_hi:[1,0,1]
	v_pk_fma_f32 v[108:109], v[96:97], 0.5, v[108:109] op_sel_hi:[1,0,1]
	v_mul_f32_e32 v97, v99, v99
	v_mul_f32_e32 v96, v109, v109
	v_fmac_f32_e32 v96, v108, v108
	v_fmac_f32_e32 v97, v98, v98
	v_add_f32_e32 v105, v121, v105
	v_add_f32_e32 v96, v96, v97
	v_add_f32_e32 v96, v105, v96
	v_mov_b32_e32 v97, v96
	s_nop 1
	v_permlane16_swap_b32_e32 v97, v96
	v_cvt_pk_bf16_f32 v100, v100, v101
	v_cvt_pk_bf16_f32 v101, v102, v103
	v_cvt_pk_bf16_f32 v105, v106, v107
	global_store_dwordx2 v[122:123], v[100:101], off offset:256
	s_waitcnt lgkmcnt(0)
	v_add_f32_e32 v96, v96, v97
	v_mov_b32_e32 v97, v96
	s_nop 1
	v_permlane32_swap_b32_e32 v97, v96
	v_cvt_pk_bf16_f32 v100, v108, v109
	v_cvt_pk_bf16_f32 v101, v98, v99
	global_store_dwordx2 v[122:123], v[104:105], off offset:32
	global_store_dwordx2 v[122:123], v[100:101], off offset:288
	s_and_saveexec_b64 s[28:29], s[38:39]
	s_cbranch_execz .LBB0_1406
	s_waitcnt lgkmcnt(0)
	v_add_f32_e32 v96, v96, v97
	ds_write_b32 v163, v96
.LBB0_1406:
	s_or_b64 exec, exec, s[28:29]
	s_waitcnt vmcnt(7)
	v_lshlrev_b32_e32 v106, 16, v118
	v_add_u32_e32 v144, 0x4000, v120
	s_waitcnt lgkmcnt(0)
	v_lshl_add_u64 v[96:97], v[144:145], 1, s[54:55]
	global_load_dwordx2 v[102:103], v[96:97], off
	global_load_dwordx2 v[100:101], v[96:97], off offset:32
	global_load_dwordx2 v[98:99], v[96:97], off offset:256
	s_nop 0
	global_load_dwordx2 v[96:97], v[96:97], off offset:288
	v_and_b32_e32 v107, 0xffff0000, v118
	v_lshlrev_b32_e32 v108, 16, v119
	v_and_b32_e32 v109, 0xffff0000, v119
	v_pk_fma_f32 v[92:93], v[92:93], 0.5, v[106:107] op_sel_hi:[1,0,1]
	v_mov_b32_e32 v121, v145
	v_pk_fma_f32 v[94:95], v[94:95], 0.5, v[108:109] op_sel_hi:[1,0,1]
	v_mul_f32_e32 v106, v93, v93
	v_lshl_add_u64 v[104:105], v[120:121], 1, s[54:55]
	v_fmac_f32_e32 v106, v92, v92
	v_mul_f32_e32 v107, v95, v95
	v_cvt_pk_bf16_f32 v92, v92, v93
	v_cvt_pk_bf16_f32 v93, v94, v95
	v_fmac_f32_e32 v107, v94, v94
	global_store_dwordx2 v[104:105], v[92:93], off
	s_waitcnt vmcnt(11)
	v_lshlrev_b32_e32 v92, 16, v116
	v_and_b32_e32 v93, 0xffff0000, v116
	v_lshlrev_b32_e32 v94, 16, v117
	v_and_b32_e32 v95, 0xffff0000, v117
	v_pk_fma_f32 v[90:91], v[90:91], 0.5, v[94:95] op_sel_hi:[1,0,1]
	v_pk_fma_f32 v[88:89], v[88:89], 0.5, v[92:93] op_sel_hi:[1,0,1]
	v_mul_f32_e32 v93, v91, v91
	v_mul_f32_e32 v92, v89, v89
	v_fmac_f32_e32 v92, v88, v88
	v_fmac_f32_e32 v93, v90, v90
	v_add_f32_e32 v106, v106, v107
	v_add_f32_e32 v92, v92, v93
	v_add_f32_e32 v106, v106, v92
	s_waitcnt vmcnt(10)
	v_lshlrev_b32_e32 v92, 16, v114
	v_and_b32_e32 v93, 0xffff0000, v114
	v_lshlrev_b32_e32 v94, 16, v115
	v_and_b32_e32 v95, 0xffff0000, v115
	v_pk_fma_f32 v[86:87], v[86:87], 0.5, v[94:95] op_sel_hi:[1,0,1]
	v_pk_fma_f32 v[84:85], v[84:85], 0.5, v[92:93] op_sel_hi:[1,0,1]
	v_cvt_pk_bf16_f32 v88, v88, v89
	v_mul_f32_e32 v89, v85, v85
	v_mul_f32_e32 v92, v87, v87
	v_fmac_f32_e32 v89, v84, v84
	v_fmac_f32_e32 v92, v86, v86
	v_add_f32_e32 v89, v89, v92
	s_waitcnt vmcnt(9)
	v_lshlrev_b32_e32 v92, 16, v112
	v_and_b32_e32 v93, 0xffff0000, v112
	v_lshlrev_b32_e32 v94, 16, v113
	v_and_b32_e32 v95, 0xffff0000, v113
	v_pk_fma_f32 v[82:83], v[82:83], 0.5, v[94:95] op_sel_hi:[1,0,1]
	v_pk_fma_f32 v[92:93], v[80:81], 0.5, v[92:93] op_sel_hi:[1,0,1]
	v_mul_f32_e32 v81, v83, v83
	v_mul_f32_e32 v80, v93, v93
	v_fmac_f32_e32 v80, v92, v92
	v_fmac_f32_e32 v81, v82, v82
	v_add_f32_e32 v89, v106, v89
	v_add_f32_e32 v80, v80, v81
	v_add_f32_e32 v80, v89, v80
	v_mov_b32_e32 v81, v80
	s_nop 1
	v_permlane16_swap_b32_e32 v81, v80
	v_cvt_pk_bf16_f32 v84, v84, v85
	v_cvt_pk_bf16_f32 v85, v86, v87
	v_cvt_pk_bf16_f32 v89, v90, v91
	global_store_dwordx2 v[104:105], v[84:85], off offset:256
	s_waitcnt lgkmcnt(0)
	v_add_f32_e32 v80, v80, v81
	v_mov_b32_e32 v81, v80
	s_nop 1
	v_permlane32_swap_b32_e32 v81, v80
	v_cvt_pk_bf16_f32 v84, v92, v93
	v_cvt_pk_bf16_f32 v85, v82, v83
	global_store_dwordx2 v[104:105], v[88:89], off offset:32
	global_store_dwordx2 v[104:105], v[84:85], off offset:288
	s_and_saveexec_b64 s[28:29], s[38:39]
	v_readlane_b32 s60, v255, 5
	v_readlane_b32 s61, v255, 6
	s_cbranch_execz .LBB0_1408
	s_waitcnt lgkmcnt(0)
	v_add_f32_e32 v80, v80, v81
	ds_write_b32 v164, v80
.LBB0_1408:
	s_or_b64 exec, exec, s[28:29]
	v_mov_b32_e32 v89, v145
	v_add_u32_e32 v88, 0x14000, v144
	s_waitcnt lgkmcnt(0)
	v_lshl_add_u64 v[80:81], v[88:89], 1, s[54:55]
	global_load_dwordx2 v[86:87], v[80:81], off
	global_load_dwordx2 v[84:85], v[80:81], off offset:32
	global_load_dwordx2 v[82:83], v[80:81], off offset:256
	s_nop 0
	global_load_dwordx2 v[80:81], v[80:81], off offset:288
	s_waitcnt vmcnt(11)
	v_lshlrev_b32_e32 v92, 16, v102
	v_and_b32_e32 v93, 0xffff0000, v102
	v_lshlrev_b32_e32 v94, 16, v103
	v_and_b32_e32 v95, 0xffff0000, v103
	v_pk_fma_f32 v[76:77], v[76:77], 0.5, v[92:93] op_sel_hi:[1,0,1]
	v_pk_fma_f32 v[78:79], v[78:79], 0.5, v[94:95] op_sel_hi:[1,0,1]
	v_mul_f32_e32 v89, v77, v77
	v_lshl_add_u64 v[90:91], v[144:145], 1, s[54:55]
	v_fmac_f32_e32 v89, v76, v76
	v_mul_f32_e32 v92, v79, v79
	v_cvt_pk_bf16_f32 v76, v76, v77
	v_cvt_pk_bf16_f32 v77, v78, v79
	v_fmac_f32_e32 v92, v78, v78
	global_store_dwordx2 v[90:91], v[76:77], off
	s_waitcnt vmcnt(11)
	v_lshlrev_b32_e32 v76, 16, v100
	v_and_b32_e32 v77, 0xffff0000, v100
	v_lshlrev_b32_e32 v78, 16, v101
	v_and_b32_e32 v79, 0xffff0000, v101
	v_pk_fma_f32 v[74:75], v[74:75], 0.5, v[78:79] op_sel_hi:[1,0,1]
	v_pk_fma_f32 v[72:73], v[72:73], 0.5, v[76:77] op_sel_hi:[1,0,1]
	v_mul_f32_e32 v77, v75, v75
	v_mul_f32_e32 v76, v73, v73
	v_fmac_f32_e32 v76, v72, v72
	v_fmac_f32_e32 v77, v74, v74
	v_add_f32_e32 v89, v89, v92
	v_add_f32_e32 v76, v76, v77
	v_add_f32_e32 v89, v89, v76
	s_waitcnt vmcnt(10)
	v_lshlrev_b32_e32 v76, 16, v98
	v_and_b32_e32 v77, 0xffff0000, v98
	v_lshlrev_b32_e32 v78, 16, v99
	v_and_b32_e32 v79, 0xffff0000, v99
	v_pk_fma_f32 v[70:71], v[70:71], 0.5, v[78:79] op_sel_hi:[1,0,1]
	v_pk_fma_f32 v[68:69], v[68:69], 0.5, v[76:77] op_sel_hi:[1,0,1]
	v_cvt_pk_bf16_f32 v72, v72, v73
	v_mul_f32_e32 v73, v69, v69
	v_mul_f32_e32 v76, v71, v71
	v_fmac_f32_e32 v73, v68, v68
	v_fmac_f32_e32 v76, v70, v70
	v_add_f32_e32 v73, v73, v76
	s_waitcnt vmcnt(9)
	v_lshlrev_b32_e32 v76, 16, v96
	v_and_b32_e32 v77, 0xffff0000, v96
	v_lshlrev_b32_e32 v78, 16, v97
	v_and_b32_e32 v79, 0xffff0000, v97
	v_pk_fma_f32 v[66:67], v[66:67], 0.5, v[78:79] op_sel_hi:[1,0,1]
	v_pk_fma_f32 v[76:77], v[64:65], 0.5, v[76:77] op_sel_hi:[1,0,1]
	v_mul_f32_e32 v65, v67, v67
	v_mul_f32_e32 v64, v77, v77
	v_fmac_f32_e32 v64, v76, v76
	v_fmac_f32_e32 v65, v66, v66
	v_add_f32_e32 v73, v89, v73
	v_add_f32_e32 v64, v64, v65
	v_add_f32_e32 v64, v73, v64
	v_mov_b32_e32 v65, v64
	s_nop 1
	v_permlane16_swap_b32_e32 v65, v64
	v_cvt_pk_bf16_f32 v68, v68, v69
	v_cvt_pk_bf16_f32 v69, v70, v71
	v_cvt_pk_bf16_f32 v73, v74, v75
	global_store_dwordx2 v[90:91], v[68:69], off offset:256
	s_waitcnt lgkmcnt(0)
	v_add_f32_e32 v64, v64, v65
	v_mov_b32_e32 v65, v64
	s_nop 1
	v_permlane32_swap_b32_e32 v65, v64
	v_cvt_pk_bf16_f32 v68, v76, v77
	v_cvt_pk_bf16_f32 v69, v66, v67
	global_store_dwordx2 v[90:91], v[72:73], off offset:32
	global_store_dwordx2 v[90:91], v[68:69], off offset:288
	s_and_saveexec_b64 s[28:29], s[38:39]
	s_cbranch_execz .LBB0_1410
	s_waitcnt lgkmcnt(0)
	v_add_f32_e32 v64, v64, v65
	ds_write_b32 v165, v64
.LBB0_1410:
	s_or_b64 exec, exec, s[28:29]
	s_waitcnt vmcnt(7)
	v_lshlrev_b32_e32 v74, 16, v86
	v_add_u32_e32 v144, 0x4000, v88
	s_waitcnt lgkmcnt(0)
	v_lshl_add_u64 v[64:65], v[144:145], 1, s[54:55]
	global_load_dwordx2 v[70:71], v[64:65], off
	global_load_dwordx2 v[68:69], v[64:65], off offset:32
	global_load_dwordx2 v[66:67], v[64:65], off offset:256
	s_nop 0
	global_load_dwordx2 v[64:65], v[64:65], off offset:288
	v_and_b32_e32 v75, 0xffff0000, v86
	v_lshlrev_b32_e32 v76, 16, v87
	v_and_b32_e32 v77, 0xffff0000, v87
	v_pk_fma_f32 v[60:61], v[60:61], 0.5, v[74:75] op_sel_hi:[1,0,1]
	v_mov_b32_e32 v89, v145
	v_pk_fma_f32 v[62:63], v[62:63], 0.5, v[76:77] op_sel_hi:[1,0,1]
	v_mul_f32_e32 v74, v61, v61
	v_lshl_add_u64 v[72:73], v[88:89], 1, s[54:55]
	v_fmac_f32_e32 v74, v60, v60
	v_mul_f32_e32 v75, v63, v63
	v_cvt_pk_bf16_f32 v60, v60, v61
	v_cvt_pk_bf16_f32 v61, v62, v63
	v_fmac_f32_e32 v75, v62, v62
	global_store_dwordx2 v[72:73], v[60:61], off
	s_waitcnt vmcnt(11)
	v_lshlrev_b32_e32 v60, 16, v84
	v_and_b32_e32 v61, 0xffff0000, v84
	v_lshlrev_b32_e32 v62, 16, v85
	v_and_b32_e32 v63, 0xffff0000, v85
	v_pk_fma_f32 v[58:59], v[58:59], 0.5, v[62:63] op_sel_hi:[1,0,1]
	v_pk_fma_f32 v[56:57], v[56:57], 0.5, v[60:61] op_sel_hi:[1,0,1]
	v_mul_f32_e32 v61, v59, v59
	v_mul_f32_e32 v60, v57, v57
	v_fmac_f32_e32 v60, v56, v56
	v_fmac_f32_e32 v61, v58, v58
	v_add_f32_e32 v74, v74, v75
	v_add_f32_e32 v60, v60, v61
	v_add_f32_e32 v74, v74, v60
	s_waitcnt vmcnt(10)
	v_lshlrev_b32_e32 v60, 16, v82
	v_and_b32_e32 v61, 0xffff0000, v82
	v_lshlrev_b32_e32 v62, 16, v83
	v_and_b32_e32 v63, 0xffff0000, v83
	v_pk_fma_f32 v[54:55], v[54:55], 0.5, v[62:63] op_sel_hi:[1,0,1]
	v_pk_fma_f32 v[52:53], v[52:53], 0.5, v[60:61] op_sel_hi:[1,0,1]
	v_cvt_pk_bf16_f32 v56, v56, v57
	v_mul_f32_e32 v57, v53, v53
	v_mul_f32_e32 v60, v55, v55
	v_fmac_f32_e32 v57, v52, v52
	v_fmac_f32_e32 v60, v54, v54
	v_add_f32_e32 v57, v57, v60
	s_waitcnt vmcnt(9)
	v_lshlrev_b32_e32 v60, 16, v80
	v_and_b32_e32 v61, 0xffff0000, v80
	v_lshlrev_b32_e32 v62, 16, v81
	v_and_b32_e32 v63, 0xffff0000, v81
	v_pk_fma_f32 v[50:51], v[50:51], 0.5, v[62:63] op_sel_hi:[1,0,1]
	v_pk_fma_f32 v[60:61], v[48:49], 0.5, v[60:61] op_sel_hi:[1,0,1]
	v_mul_f32_e32 v49, v51, v51
	v_mul_f32_e32 v48, v61, v61
	v_fmac_f32_e32 v48, v60, v60
	v_fmac_f32_e32 v49, v50, v50
	v_add_f32_e32 v57, v74, v57
	v_add_f32_e32 v48, v48, v49
	v_add_f32_e32 v48, v57, v48
	v_mov_b32_e32 v49, v48
	s_nop 1
	v_permlane16_swap_b32_e32 v49, v48
	v_cvt_pk_bf16_f32 v52, v52, v53
	v_cvt_pk_bf16_f32 v53, v54, v55
	v_cvt_pk_bf16_f32 v57, v58, v59
	global_store_dwordx2 v[72:73], v[52:53], off offset:256
	s_waitcnt lgkmcnt(0)
	v_add_f32_e32 v48, v48, v49
	v_mov_b32_e32 v49, v48
	s_nop 1
	v_permlane32_swap_b32_e32 v49, v48
	v_cvt_pk_bf16_f32 v52, v60, v61
	v_cvt_pk_bf16_f32 v53, v50, v51
	global_store_dwordx2 v[72:73], v[56:57], off offset:32
	global_store_dwordx2 v[72:73], v[52:53], off offset:288
	s_and_saveexec_b64 s[28:29], s[38:39]
	s_cbranch_execz .LBB0_1412
	s_waitcnt lgkmcnt(0)
	v_add_f32_e32 v48, v48, v49
	ds_write_b32 v166, v48
.LBB0_1412:
	s_or_b64 exec, exec, s[28:29]
	v_mov_b32_e32 v57, v145
	v_add_u32_e32 v56, 0x4000, v144
	s_waitcnt lgkmcnt(0)
	v_lshl_add_u64 v[48:49], v[56:57], 1, s[54:55]
	global_load_dwordx2 v[54:55], v[48:49], off
	global_load_dwordx2 v[52:53], v[48:49], off offset:32
	global_load_dwordx2 v[50:51], v[48:49], off offset:256
	s_nop 0
	global_load_dwordx2 v[48:49], v[48:49], off offset:288
	s_waitcnt vmcnt(11)
	v_lshlrev_b32_e32 v60, 16, v70
	v_and_b32_e32 v61, 0xffff0000, v70
	v_lshlrev_b32_e32 v62, 16, v71
	v_and_b32_e32 v63, 0xffff0000, v71
	v_pk_fma_f32 v[44:45], v[44:45], 0.5, v[60:61] op_sel_hi:[1,0,1]
	v_pk_fma_f32 v[46:47], v[46:47], 0.5, v[62:63] op_sel_hi:[1,0,1]
	v_mul_f32_e32 v57, v45, v45
	v_lshl_add_u64 v[58:59], v[144:145], 1, s[54:55]
	v_fmac_f32_e32 v57, v44, v44
	v_mul_f32_e32 v60, v47, v47
	v_cvt_pk_bf16_f32 v44, v44, v45
	v_cvt_pk_bf16_f32 v45, v46, v47
	v_fmac_f32_e32 v60, v46, v46
	global_store_dwordx2 v[58:59], v[44:45], off
	s_waitcnt vmcnt(11)
	v_lshlrev_b32_e32 v44, 16, v68
	v_and_b32_e32 v45, 0xffff0000, v68
	v_lshlrev_b32_e32 v46, 16, v69
	v_and_b32_e32 v47, 0xffff0000, v69
	v_pk_fma_f32 v[42:43], v[42:43], 0.5, v[46:47] op_sel_hi:[1,0,1]
	v_pk_fma_f32 v[40:41], v[40:41], 0.5, v[44:45] op_sel_hi:[1,0,1]
	v_mul_f32_e32 v45, v43, v43
	v_mul_f32_e32 v44, v41, v41
	v_fmac_f32_e32 v44, v40, v40
	v_fmac_f32_e32 v45, v42, v42
	v_add_f32_e32 v57, v57, v60
	v_add_f32_e32 v44, v44, v45
	v_add_f32_e32 v57, v57, v44
	s_waitcnt vmcnt(10)
	v_lshlrev_b32_e32 v44, 16, v66
	v_and_b32_e32 v45, 0xffff0000, v66
	v_lshlrev_b32_e32 v46, 16, v67
	v_and_b32_e32 v47, 0xffff0000, v67
	v_pk_fma_f32 v[38:39], v[38:39], 0.5, v[46:47] op_sel_hi:[1,0,1]
	v_pk_fma_f32 v[36:37], v[36:37], 0.5, v[44:45] op_sel_hi:[1,0,1]
	v_cvt_pk_bf16_f32 v40, v40, v41
	v_mul_f32_e32 v41, v37, v37
	v_mul_f32_e32 v44, v39, v39
	v_fmac_f32_e32 v41, v36, v36
	v_fmac_f32_e32 v44, v38, v38
	v_add_f32_e32 v41, v41, v44
	s_waitcnt vmcnt(9)
	v_lshlrev_b32_e32 v44, 16, v64
	v_and_b32_e32 v45, 0xffff0000, v64
	v_lshlrev_b32_e32 v46, 16, v65
	v_and_b32_e32 v47, 0xffff0000, v65
	v_pk_fma_f32 v[34:35], v[34:35], 0.5, v[46:47] op_sel_hi:[1,0,1]
	v_pk_fma_f32 v[44:45], v[32:33], 0.5, v[44:45] op_sel_hi:[1,0,1]
	v_mul_f32_e32 v33, v35, v35
	v_mul_f32_e32 v32, v45, v45
	v_fmac_f32_e32 v32, v44, v44
	v_fmac_f32_e32 v33, v34, v34
	v_add_f32_e32 v41, v57, v41
	v_add_f32_e32 v32, v32, v33
	v_add_f32_e32 v32, v41, v32
	v_mov_b32_e32 v33, v32
	s_nop 1
	v_permlane16_swap_b32_e32 v33, v32
	v_cvt_pk_bf16_f32 v36, v36, v37
	v_cvt_pk_bf16_f32 v37, v38, v39
	v_cvt_pk_bf16_f32 v41, v42, v43
	global_store_dwordx2 v[58:59], v[36:37], off offset:256
	s_waitcnt lgkmcnt(0)
	v_add_f32_e32 v32, v32, v33
	v_mov_b32_e32 v33, v32
	s_nop 1
	v_permlane32_swap_b32_e32 v33, v32
	v_cvt_pk_bf16_f32 v36, v44, v45
	v_cvt_pk_bf16_f32 v37, v34, v35
	global_store_dwordx2 v[58:59], v[40:41], off offset:32
	global_store_dwordx2 v[58:59], v[36:37], off offset:288
	s_and_saveexec_b64 s[28:29], s[38:39]
	s_cbranch_execz .LBB0_1414
	s_waitcnt lgkmcnt(0)
	v_add_f32_e32 v32, v32, v33
	ds_write_b32 v167, v32
.LBB0_1414:
	s_or_b64 exec, exec, s[28:29]
	s_waitcnt vmcnt(7)
	v_lshlrev_b32_e32 v42, 16, v54
	v_add_u32_e32 v144, 0x4000, v56
	s_waitcnt lgkmcnt(0)
	v_lshl_add_u64 v[32:33], v[144:145], 1, s[54:55]
	global_load_dwordx2 v[38:39], v[32:33], off
	global_load_dwordx2 v[36:37], v[32:33], off offset:32
	global_load_dwordx2 v[34:35], v[32:33], off offset:256
	s_nop 0
	global_load_dwordx2 v[32:33], v[32:33], off offset:288
	v_and_b32_e32 v43, 0xffff0000, v54
	v_lshlrev_b32_e32 v44, 16, v55
	v_and_b32_e32 v45, 0xffff0000, v55
	v_pk_fma_f32 v[28:29], v[28:29], 0.5, v[42:43] op_sel_hi:[1,0,1]
	v_mov_b32_e32 v57, v145
	v_pk_fma_f32 v[30:31], v[30:31], 0.5, v[44:45] op_sel_hi:[1,0,1]
	v_mul_f32_e32 v42, v29, v29
	v_lshl_add_u64 v[40:41], v[56:57], 1, s[54:55]
	v_fmac_f32_e32 v42, v28, v28
	v_mul_f32_e32 v43, v31, v31
	v_cvt_pk_bf16_f32 v28, v28, v29
	v_cvt_pk_bf16_f32 v29, v30, v31
	v_fmac_f32_e32 v43, v30, v30
	global_store_dwordx2 v[40:41], v[28:29], off
	s_waitcnt vmcnt(11)
	v_lshlrev_b32_e32 v28, 16, v52
	v_and_b32_e32 v29, 0xffff0000, v52
	v_lshlrev_b32_e32 v30, 16, v53
	v_and_b32_e32 v31, 0xffff0000, v53
	v_pk_fma_f32 v[26:27], v[26:27], 0.5, v[30:31] op_sel_hi:[1,0,1]
	v_pk_fma_f32 v[24:25], v[24:25], 0.5, v[28:29] op_sel_hi:[1,0,1]
	v_mul_f32_e32 v29, v27, v27
	v_mul_f32_e32 v28, v25, v25
	v_fmac_f32_e32 v28, v24, v24
	v_fmac_f32_e32 v29, v26, v26
	v_add_f32_e32 v42, v42, v43
	v_add_f32_e32 v28, v28, v29
	v_add_f32_e32 v42, v42, v28
	s_waitcnt vmcnt(10)
	v_lshlrev_b32_e32 v28, 16, v50
	v_and_b32_e32 v29, 0xffff0000, v50
	v_lshlrev_b32_e32 v30, 16, v51
	v_and_b32_e32 v31, 0xffff0000, v51
	v_pk_fma_f32 v[22:23], v[22:23], 0.5, v[30:31] op_sel_hi:[1,0,1]
	v_pk_fma_f32 v[20:21], v[20:21], 0.5, v[28:29] op_sel_hi:[1,0,1]
	v_cvt_pk_bf16_f32 v24, v24, v25
	v_mul_f32_e32 v25, v21, v21
	v_mul_f32_e32 v28, v23, v23
	v_fmac_f32_e32 v25, v20, v20
	v_fmac_f32_e32 v28, v22, v22
	v_add_f32_e32 v25, v25, v28
	s_waitcnt vmcnt(9)
	v_lshlrev_b32_e32 v28, 16, v48
	v_and_b32_e32 v29, 0xffff0000, v48
	v_lshlrev_b32_e32 v30, 16, v49
	v_and_b32_e32 v31, 0xffff0000, v49
	v_pk_fma_f32 v[18:19], v[18:19], 0.5, v[30:31] op_sel_hi:[1,0,1]
	v_pk_fma_f32 v[28:29], v[16:17], 0.5, v[28:29] op_sel_hi:[1,0,1]
	v_mul_f32_e32 v17, v19, v19
	v_mul_f32_e32 v16, v29, v29
	v_fmac_f32_e32 v16, v28, v28
	v_fmac_f32_e32 v17, v18, v18
	v_add_f32_e32 v25, v42, v25
	v_add_f32_e32 v16, v16, v17
	v_add_f32_e32 v16, v25, v16
	v_mov_b32_e32 v17, v16
	s_nop 1
	v_permlane16_swap_b32_e32 v17, v16
	v_cvt_pk_bf16_f32 v20, v20, v21
	v_cvt_pk_bf16_f32 v21, v22, v23
	v_cvt_pk_bf16_f32 v25, v26, v27
	global_store_dwordx2 v[40:41], v[20:21], off offset:256
	s_waitcnt lgkmcnt(0)
	v_add_f32_e32 v16, v16, v17
	v_mov_b32_e32 v17, v16
	s_nop 1
	v_permlane32_swap_b32_e32 v17, v16
	v_cvt_pk_bf16_f32 v20, v28, v29
	v_cvt_pk_bf16_f32 v21, v18, v19
	global_store_dwordx2 v[40:41], v[24:25], off offset:32
	global_store_dwordx2 v[40:41], v[20:21], off offset:288
	s_and_saveexec_b64 s[28:29], s[38:39]
	s_cbranch_execz .LBB0_1416
	s_waitcnt lgkmcnt(0)
	v_add_f32_e32 v16, v16, v17
	ds_write_b32 v168, v16
.LBB0_1416:
	s_or_b64 exec, exec, s[28:29]
	s_waitcnt vmcnt(7)
	v_lshlrev_b32_e32 v16, 16, v38
	s_waitcnt lgkmcnt(0)
	v_and_b32_e32 v17, 0xffff0000, v38
	v_lshlrev_b32_e32 v18, 16, v39
	v_and_b32_e32 v19, 0xffff0000, v39
	v_pk_fma_f32 v[12:13], v[12:13], 0.5, v[16:17] op_sel_hi:[1,0,1]
	v_pk_fma_f32 v[14:15], v[14:15], 0.5, v[18:19] op_sel_hi:[1,0,1]
	v_mul_f32_e32 v16, v13, v13
	v_fmac_f32_e32 v16, v12, v12
	v_lshl_add_u64 v[20:21], v[144:145], 1, s[54:55]
	v_mul_f32_e32 v17, v15, v15
	v_cvt_pk_bf16_f32 v12, v12, v13
	v_cvt_pk_bf16_f32 v13, v14, v15
	v_fmac_f32_e32 v17, v14, v14
	global_store_dwordx2 v[20:21], v[12:13], off
	s_waitcnt vmcnt(7)
	v_lshlrev_b32_e32 v12, 16, v36
	v_and_b32_e32 v13, 0xffff0000, v36
	v_lshlrev_b32_e32 v14, 16, v37
	v_and_b32_e32 v15, 0xffff0000, v37
	v_pk_fma_f32 v[10:11], v[10:11], 0.5, v[14:15] op_sel_hi:[1,0,1]
	v_pk_fma_f32 v[8:9], v[8:9], 0.5, v[12:13] op_sel_hi:[1,0,1]
	v_mul_f32_e32 v13, v11, v11
	v_mul_f32_e32 v12, v9, v9
	v_fmac_f32_e32 v12, v8, v8
	v_fmac_f32_e32 v13, v10, v10
	v_add_f32_e32 v16, v16, v17
	v_add_f32_e32 v12, v12, v13
	v_add_f32_e32 v16, v16, v12
	s_waitcnt vmcnt(6)
	v_lshlrev_b32_e32 v12, 16, v34
	v_and_b32_e32 v13, 0xffff0000, v34
	v_lshlrev_b32_e32 v14, 16, v35
	v_and_b32_e32 v15, 0xffff0000, v35
	v_pk_fma_f32 v[6:7], v[6:7], 0.5, v[14:15] op_sel_hi:[1,0,1]
	v_pk_fma_f32 v[4:5], v[4:5], 0.5, v[12:13] op_sel_hi:[1,0,1]
	v_cvt_pk_bf16_f32 v8, v8, v9
	v_mul_f32_e32 v9, v5, v5
	v_mul_f32_e32 v12, v7, v7
	v_fmac_f32_e32 v9, v4, v4
	v_fmac_f32_e32 v12, v6, v6
	v_add_f32_e32 v9, v9, v12
	s_waitcnt vmcnt(5)
	v_lshlrev_b32_e32 v12, 16, v32
	v_and_b32_e32 v13, 0xffff0000, v32
	v_lshlrev_b32_e32 v14, 16, v33
	v_and_b32_e32 v15, 0xffff0000, v33
	v_pk_fma_f32 v[2:3], v[2:3], 0.5, v[14:15] op_sel_hi:[1,0,1]
	v_pk_fma_f32 v[12:13], v[0:1], 0.5, v[12:13] op_sel_hi:[1,0,1]
	v_mul_f32_e32 v1, v3, v3
	v_mul_f32_e32 v0, v13, v13
	v_fmac_f32_e32 v0, v12, v12
	v_fmac_f32_e32 v1, v2, v2
	v_add_f32_e32 v9, v16, v9
	v_add_f32_e32 v0, v0, v1
	v_add_f32_e32 v0, v9, v0
	v_mov_b32_e32 v1, v0
	s_nop 1
	v_permlane16_swap_b32_e32 v1, v0
	v_cvt_pk_bf16_f32 v4, v4, v5
	v_cvt_pk_bf16_f32 v5, v6, v7
	v_cvt_pk_bf16_f32 v9, v10, v11
	global_store_dwordx2 v[20:21], v[4:5], off offset:256
	s_waitcnt lgkmcnt(0)
	v_add_f32_e32 v0, v0, v1
	v_mov_b32_e32 v1, v0
	s_nop 1
	v_permlane32_swap_b32_e32 v1, v0
	v_cvt_pk_bf16_f32 v4, v12, v13
	v_cvt_pk_bf16_f32 v5, v2, v3
	global_store_dwordx2 v[20:21], v[8:9], off offset:32
	global_store_dwordx2 v[20:21], v[4:5], off offset:288
	s_and_saveexec_b64 s[28:29], s[38:39]
	s_cbranch_execz .LBB0_1418
	s_waitcnt lgkmcnt(0)
	v_add_f32_e32 v0, v0, v1
	ds_write_b32 v169, v0
